# 8-phase GEMM loops: removed the 16 no-op s_setprio 0/1 pairs sitting between the two 16-MFMA halves of each compute block (issue slots inside MFMA-paced segments)
# speedup vs baseline: 1.0101x; 1.0101x over previous
; #define PG8_STAGE(bufoff, gbase, voff) do { _Pragma("unroll") for (int _i = 0; _i < 2; ++_i) \
;         __builtin_amdgcn_global_load_lds((const unsigned*)((const char*)(gbase) + (voff)[_i]), (LAS unsigned*)(lds + (bufoff) + ldsw + _i * 8192), 16, 0, 0); } while (0)
; #define PG8_LDA(dst, b, h) do { _Pragma("unroll") for (int m = 0; m < 4; ++m) _Pragma("unroll") for (int k = 0; k < 2; ++k) dst[m][k] = *(const LAS bf16x8*)(lds + PG8_SA(b, h) + aoff + m * 2048 + k * 1024); } while (0)
; #define PG8_LDB(dst, b, h) do { _Pragma("unroll") for (int n = 0; n < 2; ++n) _Pragma("unroll") for (int k = 0; k < 2; ++k) dst[n][k] = *(const LAS bf16x8*)(lds + PG8_SB(b, h) + boff + n * 2048 + k * 1024); } while (0)
; #define PG8_MMA(ai, bj, At, Bt) do { __builtin_amdgcn_s_setprio(1); _Pragma("unroll") for (int m = 0; m < 4; ++m) _Pragma("unroll") for (int n = 0; n < 2; ++n) _Pragma("unroll") for (int k = 0; k < 2; ++k) \
;         acc[ai][bj][m][n] = __builtin_amdgcn_mfma_f32_16x16x32_bf16(Bt[n][k], At[m][k], acc[ai][bj][m][n], 0, 0, 0); __builtin_amdgcn_s_setprio(0); } while (0)
; #define PG8_WAIT_V(n) asm volatile("s_waitcnt vmcnt(" #n ")" ::: "memory")
; #define PG8_WAIT_L(n) asm volatile("s_waitcnt lgkmcnt(" #n ")" ::: "memory")
; #define PG8_BAR __builtin_amdgcn_s_barrier()
; #define PG8_SCHED __builtin_amdgcn_sched_barrier(0)
; template <class Epi>
; DI void gemm_phase(int wid0, LAS unsigned char* lds, const Gemm g, const StaticOrder& S, const Epi& E) {
;     ...
;             PG8_LDB(B0, 0, 0); PG8_LDB(B1, 0, 1); PG8_SCHED; PG8_LDA(At, 0, 0); PG8_STAGE(PG8_SA(1, 1), a1 + hstep, voffA);
;             PG8_WAIT_V(8); PG8_WAIT_L(0); PG8_BAR; PG8_MMA(0, 0, At, B0); PG8_MMA(0, 1, At, B1); PG8_BAR; PG8_SCHED;
;             PG8_LDA(At, 0, 1); PG8_STAGE(PG8_SB(0, 0), b2, voffB); PG8_STAGE(PG8_SB(0, 1), b2 + hstep, voffB); PG8_STAGE(PG8_SA(0, 0), a2, voffA);
.LBB0_58:
	s_add_u32 s68, s22, 0xfffc0080
	s_addc_u32 s69, s23, -1
	s_add_i32 s80, 0, 0x10000
	s_cmp_eq_u32 s79, 12
	s_cselect_b32 s71, s15, s69
	s_cselect_b32 s70, s40, s68
	v_add_u32_e32 v144, s80, v147
	s_cselect_b32 s69, s13, s67
	s_cselect_b32 s68, s41, s66
	s_add_i32 s82, 0, 0x14000
	ds_read_b128 v[140:143], v144
	ds_read_b128 v[150:153], v144 offset:1024
	ds_read_b128 v[154:157], v144 offset:2048
	ds_read_b128 v[158:161], v144 offset:3072
	v_add_u32_e32 v144, s82, v147
	ds_read_b128 v[176:179], v144
	ds_read_b128 v[180:183], v144 offset:1024
	ds_read_b128 v[190:193], v144 offset:2048
	ds_read_b128 v[194:197], v144 offset:3072
	s_add_i32 m0, s73, 0xc000
	ds_read_b128 v[198:201], v149
	ds_read_b128 v[202:205], v149 offset:1024
	ds_read_b128 v[206:209], v149 offset:2048
	ds_read_b128 v[210:213], v149 offset:3072
	ds_read_b128 v[214:217], v149 offset:4096
	ds_read_b128 v[218:221], v149 offset:5120
	ds_read_b128 v[222:225], v149 offset:6144
	ds_read_b128 v[226:229], v149 offset:7168
	global_load_lds_dwordx4 v136, s[22:23]
	s_add_i32 m0, s73, 0xe000
	s_nop 0
	global_load_lds_dwordx4 v138, s[22:23]
	s_waitcnt vmcnt(8)
	s_waitcnt lgkmcnt(0)
	s_barrier
	s_setprio 1
	s_waitcnt lgkmcnt(0)
	v_mfma_f32_16x16x32_bf16 v[126:129], v[140:143], v[198:201], v[126:129]
	v_mfma_f32_16x16x32_bf16 v[122:125], v[154:157], v[198:201], v[122:125]
	v_mfma_f32_16x16x32_bf16 v[110:113], v[140:143], v[206:209], v[110:113]
	v_mfma_f32_16x16x32_bf16 v[106:109], v[154:157], v[206:209], v[106:109]
	v_mfma_f32_16x16x32_bf16 v[94:97], v[140:143], v[214:217], v[94:97]
	v_mfma_f32_16x16x32_bf16 v[90:93], v[154:157], v[214:217], v[90:93]
	v_mfma_f32_16x16x32_bf16 v[78:81], v[140:143], v[222:225], v[78:81]
	v_mfma_f32_16x16x32_bf16 v[74:77], v[154:157], v[222:225], v[74:77]
	v_mfma_f32_16x16x32_bf16 v[126:129], v[150:153], v[202:205], v[126:129]
	v_mfma_f32_16x16x32_bf16 v[122:125], v[158:161], v[202:205], v[122:125]
	v_mfma_f32_16x16x32_bf16 v[110:113], v[150:153], v[210:213], v[110:113]
	v_mfma_f32_16x16x32_bf16 v[106:109], v[158:161], v[210:213], v[106:109]
	v_mfma_f32_16x16x32_bf16 v[94:97], v[150:153], v[218:221], v[94:97]
	v_mfma_f32_16x16x32_bf16 v[90:93], v[158:161], v[218:221], v[90:93]
	v_mfma_f32_16x16x32_bf16 v[78:81], v[150:153], v[226:229], v[78:81]
	v_mfma_f32_16x16x32_bf16 v[74:77], v[158:161], v[226:229], v[74:77]
	v_mfma_f32_16x16x32_bf16 v[118:121], v[176:179], v[198:201], v[118:121]
	v_mfma_f32_16x16x32_bf16 v[114:117], v[190:193], v[198:201], v[114:117]
	v_mfma_f32_16x16x32_bf16 v[102:105], v[176:179], v[206:209], v[102:105]
	v_mfma_f32_16x16x32_bf16 v[98:101], v[190:193], v[206:209], v[98:101]
	v_mfma_f32_16x16x32_bf16 v[86:89], v[176:179], v[214:217], v[86:89]
	v_mfma_f32_16x16x32_bf16 v[82:85], v[190:193], v[214:217], v[82:85]
	v_mfma_f32_16x16x32_bf16 v[70:73], v[176:179], v[222:225], v[70:73]
	v_mfma_f32_16x16x32_bf16 v[66:69], v[190:193], v[222:225], v[66:69]
	v_mfma_f32_16x16x32_bf16 v[118:121], v[180:183], v[202:205], v[118:121]
	v_mfma_f32_16x16x32_bf16 v[114:117], v[194:197], v[202:205], v[114:117]
	v_mfma_f32_16x16x32_bf16 v[102:105], v[180:183], v[210:213], v[102:105]
	v_mfma_f32_16x16x32_bf16 v[98:101], v[194:197], v[210:213], v[98:101]
	v_mfma_f32_16x16x32_bf16 v[86:89], v[180:183], v[218:221], v[86:89]
	v_mfma_f32_16x16x32_bf16 v[82:85], v[194:197], v[218:221], v[82:85]
	v_mfma_f32_16x16x32_bf16 v[70:73], v[180:183], v[226:229], v[70:73]
	v_mfma_f32_16x16x32_bf16 v[66:69], v[194:197], v[226:229], v[66:69]
	s_setprio 0
	s_barrier
	s_add_i32 s80, s80, s72
	v_lshl_add_u64 v[144:145], s[68:69], 0, v[0:1]
	s_mov_b32 m0, s80
	ds_read_b128 v[198:201], v149 offset:16384
	ds_read_b128 v[202:205], v149 offset:17408
	ds_read_b128 v[206:209], v149 offset:18432
	ds_read_b128 v[210:213], v149 offset:19456
	ds_read_b128 v[214:217], v149 offset:20480
	ds_read_b128 v[218:221], v149 offset:21504
	ds_read_b128 v[222:225], v149 offset:22528
	ds_read_b128 v[226:229], v149 offset:23552
	global_load_lds_dwordx4 v[144:145], off
	s_add_i32 m0, s80, 0x2000
	s_add_u32 s80, s68, 0x40000
	v_lshl_add_u64 v[162:163], s[68:69], 0, v[130:131]
	s_addc_u32 s81, s69, 0
	s_add_i32 s82, s82, s72
	global_load_lds_dwordx4 v[162:163], off
	s_mov_b32 m0, s82
	v_lshl_add_u64 v[236:237], s[70:71], 0, v[132:133]
	global_load_lds_dwordx4 v0, s[80:81]
	s_add_i32 m0, s82, 0x2000
	s_nop 0
	global_load_lds_dwordx4 v130, s[80:81]
	v_lshl_add_u64 v[230:231], s[70:71], 0, v[134:135]
	s_mov_b32 m0, s73
	s_nop 0
	global_load_lds_dwordx4 v[230:231], off
	s_mov_b32 m0, s74
	s_nop 0
	global_load_lds_dwordx4 v[236:237], off
	s_waitcnt vmcnt(8)
	s_waitcnt lgkmcnt(0)
	s_barrier
; #define PG8_STAGE(bufoff, gbase, voff) do { _Pragma("unroll") for (int _i = 0; _i < 2; ++_i) \
;         __builtin_amdgcn_global_load_lds((const unsigned*)((const char*)(gbase) + (voff)[_i]), (LAS unsigned*)(lds + (bufoff) + ldsw + _i * 8192), 16, 0, 0); } while (0)
; #define PG8_LDA(dst, b, h) do { _Pragma("unroll") for (int m = 0; m < 4; ++m) _Pragma("unroll") for (int k = 0; k < 2; ++k) dst[m][k] = *(const LAS bf16x8*)(lds + PG8_SA(b, h) + aoff + m * 2048 + k * 1024); } while (0)
; #define PG8_LDB(dst, b, h) do { _Pragma("unroll") for (int n = 0; n < 2; ++n) _Pragma("unroll") for (int k = 0; k < 2; ++k) dst[n][k] = *(const LAS bf16x8*)(lds + PG8_SB(b, h) + boff + n * 2048 + k * 1024); } while (0)
; #define PG8_MMA(ai, bj, At, Bt) do { __builtin_amdgcn_s_setprio(1); _Pragma("unroll") for (int m = 0; m < 4; ++m) _Pragma("unroll") for (int n = 0; n < 2; ++n) _Pragma("unroll") for (int k = 0; k < 2; ++k) \
;         acc[ai][bj][m][n] = __builtin_amdgcn_mfma_f32_16x16x32_bf16(Bt[n][k], At[m][k], acc[ai][bj][m][n], 0, 0, 0); __builtin_amdgcn_s_setprio(0); } while (0)
; #define PG8_WAIT_V(n) asm volatile("s_waitcnt vmcnt(" #n ")" ::: "memory")
; #define PG8_WAIT_L(n) asm volatile("s_waitcnt lgkmcnt(" #n ")" ::: "memory")
; #define PG8_BAR __builtin_amdgcn_s_barrier()
; #define PG8_SCHED __builtin_amdgcn_sched_barrier(0)
; template <class Epi>
; DI void gemm_phase(int wid0, LAS unsigned char* lds, const Gemm g, const StaticOrder& S, const Epi& E) {
;     ...
;             PG8_WAIT_V(8); PG8_WAIT_L(0); PG8_BAR; PG8_MMA(1, 0, At, B0); PG8_MMA(1, 1, At, B1); PG8_BAR; PG8_SCHED;
;             PG8_LDB(B0, 1, 0); PG8_LDB(B1, 1, 1); PG8_SCHED; PG8_LDA(At, 1, 0); PG8_STAGE(PG8_SA(0, 1), a2 + hstep, voffA);
;             PG8_WAIT_V(8); PG8_WAIT_L(0); PG8_BAR; PG8_MMA(0, 0, At, B0); PG8_MMA(0, 1, At, B1); PG8_BAR; PG8_SCHED;
	s_setprio 1
	s_waitcnt lgkmcnt(0)
	v_mfma_f32_16x16x32_bf16 v[62:65], v[140:143], v[198:201], v[62:65]
	v_mfma_f32_16x16x32_bf16 v[58:61], v[154:157], v[198:201], v[58:61]
	v_mfma_f32_16x16x32_bf16 v[46:49], v[140:143], v[206:209], v[46:49]
	v_mfma_f32_16x16x32_bf16 v[42:45], v[154:157], v[206:209], v[42:45]
	v_mfma_f32_16x16x32_bf16 v[30:33], v[140:143], v[214:217], v[30:33]
	v_mfma_f32_16x16x32_bf16 v[26:29], v[154:157], v[214:217], v[26:29]
	v_mfma_f32_16x16x32_bf16 v[14:17], v[140:143], v[222:225], v[14:17]
	v_mfma_f32_16x16x32_bf16 v[10:13], v[154:157], v[222:225], v[10:13]
	v_mfma_f32_16x16x32_bf16 v[62:65], v[150:153], v[202:205], v[62:65]
	v_mfma_f32_16x16x32_bf16 v[58:61], v[158:161], v[202:205], v[58:61]
	v_mfma_f32_16x16x32_bf16 v[46:49], v[150:153], v[210:213], v[46:49]
	v_mfma_f32_16x16x32_bf16 v[42:45], v[158:161], v[210:213], v[42:45]
	v_mfma_f32_16x16x32_bf16 v[30:33], v[150:153], v[218:221], v[30:33]
	v_mfma_f32_16x16x32_bf16 v[26:29], v[158:161], v[218:221], v[26:29]
	v_mfma_f32_16x16x32_bf16 v[14:17], v[150:153], v[226:229], v[14:17]
	v_mfma_f32_16x16x32_bf16 v[10:13], v[158:161], v[226:229], v[10:13]
	v_mfma_f32_16x16x32_bf16 v[54:57], v[176:179], v[198:201], v[54:57]
	v_mfma_f32_16x16x32_bf16 v[50:53], v[190:193], v[198:201], v[50:53]
	v_mfma_f32_16x16x32_bf16 v[38:41], v[176:179], v[206:209], v[38:41]
	v_mfma_f32_16x16x32_bf16 v[34:37], v[190:193], v[206:209], v[34:37]
	v_mfma_f32_16x16x32_bf16 v[22:25], v[176:179], v[214:217], v[22:25]
	v_mfma_f32_16x16x32_bf16 v[18:21], v[190:193], v[214:217], v[18:21]
	v_mfma_f32_16x16x32_bf16 v[6:9], v[176:179], v[222:225], v[6:9]
	v_mfma_f32_16x16x32_bf16 v[2:5], v[190:193], v[222:225], v[2:5]
	v_mfma_f32_16x16x32_bf16 v[54:57], v[180:183], v[202:205], v[54:57]
	v_mfma_f32_16x16x32_bf16 v[50:53], v[194:197], v[202:205], v[50:53]
	v_mfma_f32_16x16x32_bf16 v[38:41], v[180:183], v[210:213], v[38:41]
	v_mfma_f32_16x16x32_bf16 v[34:37], v[194:197], v[210:213], v[34:37]
	v_mfma_f32_16x16x32_bf16 v[22:25], v[180:183], v[218:221], v[22:25]
	v_mfma_f32_16x16x32_bf16 v[18:21], v[194:197], v[218:221], v[18:21]
	v_mfma_f32_16x16x32_bf16 v[6:9], v[180:183], v[226:229], v[6:9]
	v_mfma_f32_16x16x32_bf16 v[2:5], v[194:197], v[226:229], v[2:5]
	s_setprio 0
	s_barrier
	s_add_i32 s80, 0, 0x18000
	s_add_i32 s81, 0, 0x1c000
	v_add_u32_e32 v158, s80, v147
	v_add_u32_e32 v189, s81, v147
	ds_read_b128 v[140:143], v158
	ds_read_b128 v[150:153], v158 offset:1024
	ds_read_b128 v[154:157], v158 offset:2048
	ds_read_b128 v[158:161], v158 offset:3072
	ds_read_b128 v[176:179], v189
	ds_read_b128 v[180:183], v189 offset:1024
	ds_read_b128 v[190:193], v189 offset:2048
	ds_read_b128 v[194:197], v189 offset:3072
	s_add_u32 s70, s70, 0x40000
	s_addc_u32 s71, s71, 0
	s_mov_b32 m0, s75
	ds_read_b128 v[198:201], v149 offset:32768
	ds_read_b128 v[202:205], v149 offset:33792
	ds_read_b128 v[206:209], v149 offset:34816
	ds_read_b128 v[210:213], v149 offset:35840
	ds_read_b128 v[214:217], v149 offset:36864
	ds_read_b128 v[218:221], v149 offset:37888
	ds_read_b128 v[222:225], v149 offset:38912
	ds_read_b128 v[226:229], v149 offset:39936
	global_load_lds_dwordx4 v134, s[70:71]
	v_lshl_add_u64 v[238:239], s[70:71], 0, v[132:133]
	s_mov_b32 m0, s76
	s_nop 0
	global_load_lds_dwordx4 v[238:239], off
	s_waitcnt vmcnt(8)
	s_waitcnt lgkmcnt(0)
	s_barrier
	s_setprio 1
	s_waitcnt lgkmcnt(0)
	v_mfma_f32_16x16x32_bf16 v[126:129], v[140:143], v[198:201], v[126:129]
	v_mfma_f32_16x16x32_bf16 v[122:125], v[154:157], v[198:201], v[122:125]
	v_mfma_f32_16x16x32_bf16 v[110:113], v[140:143], v[206:209], v[110:113]
	v_mfma_f32_16x16x32_bf16 v[106:109], v[154:157], v[206:209], v[106:109]
	v_mfma_f32_16x16x32_bf16 v[94:97], v[140:143], v[214:217], v[94:97]
	v_mfma_f32_16x16x32_bf16 v[90:93], v[154:157], v[214:217], v[90:93]
	v_mfma_f32_16x16x32_bf16 v[78:81], v[140:143], v[222:225], v[78:81]
	v_mfma_f32_16x16x32_bf16 v[74:77], v[154:157], v[222:225], v[74:77]
	v_mfma_f32_16x16x32_bf16 v[126:129], v[150:153], v[202:205], v[126:129]
	v_mfma_f32_16x16x32_bf16 v[122:125], v[158:161], v[202:205], v[122:125]
	v_mfma_f32_16x16x32_bf16 v[110:113], v[150:153], v[210:213], v[110:113]
	v_mfma_f32_16x16x32_bf16 v[106:109], v[158:161], v[210:213], v[106:109]
	v_mfma_f32_16x16x32_bf16 v[94:97], v[150:153], v[218:221], v[94:97]
	v_mfma_f32_16x16x32_bf16 v[90:93], v[158:161], v[218:221], v[90:93]
	v_mfma_f32_16x16x32_bf16 v[78:81], v[150:153], v[226:229], v[78:81]
	v_mfma_f32_16x16x32_bf16 v[74:77], v[158:161], v[226:229], v[74:77]
	v_mfma_f32_16x16x32_bf16 v[118:121], v[176:179], v[198:201], v[118:121]
	v_mfma_f32_16x16x32_bf16 v[114:117], v[190:193], v[198:201], v[114:117]
	v_mfma_f32_16x16x32_bf16 v[102:105], v[176:179], v[206:209], v[102:105]
	v_mfma_f32_16x16x32_bf16 v[98:101], v[190:193], v[206:209], v[98:101]
	v_mfma_f32_16x16x32_bf16 v[86:89], v[176:179], v[214:217], v[86:89]
	v_mfma_f32_16x16x32_bf16 v[82:85], v[190:193], v[214:217], v[82:85]
	v_mfma_f32_16x16x32_bf16 v[70:73], v[176:179], v[222:225], v[70:73]
	v_mfma_f32_16x16x32_bf16 v[66:69], v[190:193], v[222:225], v[66:69]
	v_mfma_f32_16x16x32_bf16 v[118:121], v[180:183], v[202:205], v[118:121]
	v_mfma_f32_16x16x32_bf16 v[114:117], v[194:197], v[202:205], v[114:117]
	v_mfma_f32_16x16x32_bf16 v[102:105], v[180:183], v[210:213], v[102:105]
	v_mfma_f32_16x16x32_bf16 v[98:101], v[194:197], v[210:213], v[98:101]
	v_mfma_f32_16x16x32_bf16 v[86:89], v[180:183], v[218:221], v[86:89]
	v_mfma_f32_16x16x32_bf16 v[82:85], v[194:197], v[218:221], v[82:85]
	v_mfma_f32_16x16x32_bf16 v[70:73], v[180:183], v[226:229], v[70:73]
	v_mfma_f32_16x16x32_bf16 v[66:69], v[194:197], v[226:229], v[66:69]
	s_setprio 0
	s_barrier
; #define PG8_STAGE(bufoff, gbase, voff) do { _Pragma("unroll") for (int _i = 0; _i < 2; ++_i) \
;         __builtin_amdgcn_global_load_lds((const unsigned*)((const char*)(gbase) + (voff)[_i]), (LAS unsigned*)(lds + (bufoff) + ldsw + _i * 8192), 16, 0, 0); } while (0)
; #define PG8_LDA(dst, b, h) do { _Pragma("unroll") for (int m = 0; m < 4; ++m) _Pragma("unroll") for (int k = 0; k < 2; ++k) dst[m][k] = *(const LAS bf16x8*)(lds + PG8_SA(b, h) + aoff + m * 2048 + k * 1024); } while (0)
; #define PG8_MMA(ai, bj, At, Bt) do { __builtin_amdgcn_s_setprio(1); _Pragma("unroll") for (int m = 0; m < 4; ++m) _Pragma("unroll") for (int n = 0; n < 2; ++n) _Pragma("unroll") for (int k = 0; k < 2; ++k) \
;         acc[ai][bj][m][n] = __builtin_amdgcn_mfma_f32_16x16x32_bf16(Bt[n][k], At[m][k], acc[ai][bj][m][n], 0, 0, 0); __builtin_amdgcn_s_setprio(0); } while (0)
; #define PG8_WAIT_V(n) asm volatile("s_waitcnt vmcnt(" #n ")" ::: "memory")
; #define PG8_WAIT_L(n) asm volatile("s_waitcnt lgkmcnt(" #n ")" ::: "memory")
; #define PG8_BAR __builtin_amdgcn_s_barrier()
; #define PG8_SCHED __builtin_amdgcn_sched_barrier(0)
; template <class Epi>
; DI void gemm_phase(int wid0, LAS unsigned char* lds, const Gemm g, const StaticOrder& S, const Epi& E) {
;     ...
;             PG8_LDA(At, 1, 1); PG8_STAGE(PG8_SB(1, 0), b3, voffB); PG8_STAGE(PG8_SB(1, 1), b3 + hstep, voffB); PG8_STAGE(PG8_SA(1, 0), a3, voffA);
;             PG8_WAIT_V(8); PG8_WAIT_L(0); PG8_BAR; PG8_MMA(1, 0, At, B0); PG8_MMA(1, 1, At, B1); PG8_BAR; PG8_SCHED;
;         }
	s_add_i32 s70, s80, s72
	v_lshl_add_u64 v[144:145], v[144:145], 0, s[30:31]
	s_mov_b32 m0, s70
	ds_read_b128 v[198:201], v149 offset:49152
	ds_read_b128 v[202:205], v149 offset:50176
	ds_read_b128 v[206:209], v149 offset:51200
	ds_read_b128 v[210:213], v149 offset:52224
	ds_read_b128 v[214:217], v149 offset:53248
	ds_read_b128 v[218:221], v149 offset:54272
	ds_read_b128 v[222:225], v149 offset:55296
	ds_read_b128 v[226:229], v149 offset:56320
	global_load_lds_dwordx4 v[144:145], off
	s_add_i32 m0, s70, 0x2000
	s_add_u32 s68, s68, 0x40080
	v_lshl_add_u64 v[144:145], v[162:163], 0, s[30:31]
	s_addc_u32 s69, s69, 0
	s_add_i32 s70, s81, s72
	global_load_lds_dwordx4 v[144:145], off
	s_mov_b32 m0, s70
	s_nop 0
	global_load_lds_dwordx4 v0, s[68:69]
	s_add_i32 m0, s70, 0x2000
	s_nop 0
	global_load_lds_dwordx4 v130, s[68:69]
	v_lshl_add_u64 v[144:145], v[230:231], 0, s[30:31]
	s_mov_b32 m0, s2
	s_nop 0
	global_load_lds_dwordx4 v[144:145], off
	v_lshl_add_u64 v[144:145], v[236:237], 0, s[30:31]
	s_mov_b32 m0, s77
	s_nop 0
	global_load_lds_dwordx4 v[144:145], off
	s_waitcnt vmcnt(8)
	s_waitcnt lgkmcnt(0)
	s_barrier
	s_setprio 1
	s_waitcnt lgkmcnt(0)
	v_mfma_f32_16x16x32_bf16 v[62:65], v[140:143], v[198:201], v[62:65]
	v_mfma_f32_16x16x32_bf16 v[58:61], v[154:157], v[198:201], v[58:61]
	v_mfma_f32_16x16x32_bf16 v[46:49], v[140:143], v[206:209], v[46:49]
	v_mfma_f32_16x16x32_bf16 v[42:45], v[154:157], v[206:209], v[42:45]
	v_mfma_f32_16x16x32_bf16 v[30:33], v[140:143], v[214:217], v[30:33]
	v_mfma_f32_16x16x32_bf16 v[26:29], v[154:157], v[214:217], v[26:29]
	v_mfma_f32_16x16x32_bf16 v[14:17], v[140:143], v[222:225], v[14:17]
	v_mfma_f32_16x16x32_bf16 v[10:13], v[154:157], v[222:225], v[10:13]
	v_mfma_f32_16x16x32_bf16 v[62:65], v[150:153], v[202:205], v[62:65]
	v_mfma_f32_16x16x32_bf16 v[58:61], v[158:161], v[202:205], v[58:61]
	v_mfma_f32_16x16x32_bf16 v[46:49], v[150:153], v[210:213], v[46:49]
	v_mfma_f32_16x16x32_bf16 v[42:45], v[158:161], v[210:213], v[42:45]
	v_mfma_f32_16x16x32_bf16 v[30:33], v[150:153], v[218:221], v[30:33]
	v_mfma_f32_16x16x32_bf16 v[26:29], v[158:161], v[218:221], v[26:29]
	v_mfma_f32_16x16x32_bf16 v[14:17], v[150:153], v[226:229], v[14:17]
	v_mfma_f32_16x16x32_bf16 v[10:13], v[158:161], v[226:229], v[10:13]
	v_mfma_f32_16x16x32_bf16 v[54:57], v[176:179], v[198:201], v[54:57]
	v_mfma_f32_16x16x32_bf16 v[50:53], v[190:193], v[198:201], v[50:53]
	v_mfma_f32_16x16x32_bf16 v[38:41], v[176:179], v[206:209], v[38:41]
	v_mfma_f32_16x16x32_bf16 v[34:37], v[190:193], v[206:209], v[34:37]
	v_mfma_f32_16x16x32_bf16 v[22:25], v[176:179], v[214:217], v[22:25]
	v_mfma_f32_16x16x32_bf16 v[18:21], v[190:193], v[214:217], v[18:21]
	v_mfma_f32_16x16x32_bf16 v[6:9], v[176:179], v[222:225], v[6:9]
	v_mfma_f32_16x16x32_bf16 v[2:5], v[190:193], v[222:225], v[2:5]
	v_mfma_f32_16x16x32_bf16 v[54:57], v[180:183], v[202:205], v[54:57]
	v_mfma_f32_16x16x32_bf16 v[50:53], v[194:197], v[202:205], v[50:53]
	v_mfma_f32_16x16x32_bf16 v[38:41], v[180:183], v[210:213], v[38:41]
	v_mfma_f32_16x16x32_bf16 v[34:37], v[194:197], v[210:213], v[34:37]
	v_mfma_f32_16x16x32_bf16 v[22:25], v[180:183], v[218:221], v[22:25]
	v_mfma_f32_16x16x32_bf16 v[18:21], v[194:197], v[218:221], v[18:21]
	v_mfma_f32_16x16x32_bf16 v[6:9], v[180:183], v[226:229], v[6:9]
	v_mfma_f32_16x16x32_bf16 v[2:5], v[194:197], v[226:229], v[2:5]
	s_setprio 0
	s_barrier
	s_add_i32 s79, s79, 2
	s_add_u32 s22, s22, 0x100
	s_addc_u32 s23, s23, 0
	s_add_u32 s66, s66, 0x100
	s_addc_u32 s67, s67, 0
	s_cmp_gt_u32 s79, 13
	s_cbranch_scc0 .LBB0_58
	s_and_b64 vcc, exec, s[10:11]
	s_movk_i32 s79, 0x3fff
	s_movk_i32 s40, 0x7fff
	v_readlane_b32 s41, v245, 48
	s_cbranch_vccz .LBB0_61
	s_barrier

; #define PG8_STAGE(bufoff, gbase, voff) do { _Pragma("unroll") for (int _i = 0; _i < 2; ++_i) \
;         __builtin_amdgcn_global_load_lds((const unsigned*)((const char*)(gbase) + (voff)[_i]), (LAS unsigned*)(lds + (bufoff) + ldsw + _i * 8192), 16, 0, 0); } while (0)
; #define PG8_LDA(dst, b, h) do { _Pragma("unroll") for (int m = 0; m < 4; ++m) _Pragma("unroll") for (int k = 0; k < 2; ++k) dst[m][k] = *(const LAS bf16x8*)(lds + PG8_SA(b, h) + aoff + m * 2048 + k * 1024); } while (0)
; #define PG8_LDB(dst, b, h) do { _Pragma("unroll") for (int n = 0; n < 2; ++n) _Pragma("unroll") for (int k = 0; k < 2; ++k) dst[n][k] = *(const LAS bf16x8*)(lds + PG8_SB(b, h) + boff + n * 2048 + k * 1024); } while (0)
; #define PG8_MMA(ai, bj, At, Bt) do { __builtin_amdgcn_s_setprio(1); _Pragma("unroll") for (int m = 0; m < 4; ++m) _Pragma("unroll") for (int n = 0; n < 2; ++n) _Pragma("unroll") for (int k = 0; k < 2; ++k) \
;         acc[ai][bj][m][n] = __builtin_amdgcn_mfma_f32_16x16x32_bf16(Bt[n][k], At[m][k], acc[ai][bj][m][n], 0, 0, 0); __builtin_amdgcn_s_setprio(0); } while (0)
; #define PG8_WAIT_V(n) asm volatile("s_waitcnt vmcnt(" #n ")" ::: "memory")
; #define PG8_WAIT_L(n) asm volatile("s_waitcnt lgkmcnt(" #n ")" ::: "memory")
; #define PG8_BAR __builtin_amdgcn_s_barrier()
; #define PG8_SCHED __builtin_amdgcn_sched_barrier(0)
; template <class Epi>
; DI void gemm_phase(int wid0, LAS unsigned char* lds, const Gemm g, const StaticOrder& S, const Epi& E) {
;     ...
;             PG8_LDB(B0, 0, 0); PG8_LDB(B1, 0, 1); PG8_SCHED; PG8_LDA(At, 0, 0); PG8_STAGE(PG8_SA(1, 1), a1 + hstep, voffA);
;             PG8_WAIT_V(8); PG8_WAIT_L(0); PG8_BAR; PG8_MMA(0, 0, At, B0); PG8_MMA(0, 1, At, B1); PG8_BAR; PG8_SCHED;
;             PG8_LDA(At, 0, 1); PG8_STAGE(PG8_SB(0, 0), b2, voffB); PG8_STAGE(PG8_SB(0, 1), b2 + hstep, voffB); PG8_STAGE(PG8_SA(0, 0), a2, voffA);
.LBB0_139:
	s_add_u32 s22, s20, 0xfffc0080
	s_addc_u32 s23, s21, -1
	s_add_i32 s72, 0, 0x10000
	s_cmp_eq_u32 s71, 12
	s_cselect_b32 s39, s15, s23
	s_cselect_b32 s38, s66, s22
	v_add_u32_e32 v0, s72, v143
	s_cselect_b32 s23, s13, s70
	s_cselect_b32 s22, s67, s69
	s_add_i32 s74, 0, 0x14000
	ds_read_b128 v[146:149], v0
	ds_read_b128 v[150:153], v0 offset:1024
	ds_read_b128 v[154:157], v0 offset:2048
	ds_read_b128 v[158:161], v0 offset:3072
	v_add_u32_e32 v0, s74, v143
	ds_read_b128 v[176:179], v0
	ds_read_b128 v[180:183], v0 offset:1024
	ds_read_b128 v[190:193], v0 offset:2048
	ds_read_b128 v[194:197], v0 offset:3072
	s_add_i32 m0, s11, 0xc000
	ds_read_b128 v[198:201], v145
	ds_read_b128 v[202:205], v145 offset:1024
	ds_read_b128 v[206:209], v145 offset:2048
	ds_read_b128 v[210:213], v145 offset:3072
	ds_read_b128 v[214:217], v145 offset:4096
	ds_read_b128 v[218:221], v145 offset:5120
	ds_read_b128 v[222:225], v145 offset:6144
	ds_read_b128 v[226:229], v145 offset:7168
	global_load_lds_dwordx4 v138, s[20:21]
	s_add_i32 m0, s11, 0xe000
	s_nop 0
	global_load_lds_dwordx4 v140, s[20:21]
	s_waitcnt vmcnt(8)
	s_waitcnt lgkmcnt(0)
	s_barrier
	s_setprio 1
	s_waitcnt lgkmcnt(0)
	v_mfma_f32_16x16x32_bf16 v[126:129], v[146:149], v[198:201], v[126:129]
	v_mfma_f32_16x16x32_bf16 v[122:125], v[154:157], v[198:201], v[122:125]
	v_mfma_f32_16x16x32_bf16 v[118:121], v[146:149], v[206:209], v[118:121]
	v_mfma_f32_16x16x32_bf16 v[114:117], v[154:157], v[206:209], v[114:117]
	v_mfma_f32_16x16x32_bf16 v[102:105], v[146:149], v[214:217], v[102:105]
	v_mfma_f32_16x16x32_bf16 v[98:101], v[154:157], v[214:217], v[98:101]
	v_mfma_f32_16x16x32_bf16 v[86:89], v[146:149], v[222:225], v[86:89]
	v_mfma_f32_16x16x32_bf16 v[82:85], v[154:157], v[222:225], v[82:85]
	v_mfma_f32_16x16x32_bf16 v[126:129], v[150:153], v[202:205], v[126:129]
	v_mfma_f32_16x16x32_bf16 v[122:125], v[158:161], v[202:205], v[122:125]
	v_mfma_f32_16x16x32_bf16 v[118:121], v[150:153], v[210:213], v[118:121]
	v_mfma_f32_16x16x32_bf16 v[114:117], v[158:161], v[210:213], v[114:117]
	v_mfma_f32_16x16x32_bf16 v[102:105], v[150:153], v[218:221], v[102:105]
	v_mfma_f32_16x16x32_bf16 v[98:101], v[158:161], v[218:221], v[98:101]
	v_mfma_f32_16x16x32_bf16 v[86:89], v[150:153], v[226:229], v[86:89]
	v_mfma_f32_16x16x32_bf16 v[82:85], v[158:161], v[226:229], v[82:85]
	v_mfma_f32_16x16x32_bf16 v[110:113], v[176:179], v[198:201], v[110:113]
	v_mfma_f32_16x16x32_bf16 v[106:109], v[190:193], v[198:201], v[106:109]
	v_mfma_f32_16x16x32_bf16 v[94:97], v[176:179], v[206:209], v[94:97]
	v_mfma_f32_16x16x32_bf16 v[90:93], v[190:193], v[206:209], v[90:93]
	v_mfma_f32_16x16x32_bf16 v[78:81], v[176:179], v[214:217], v[78:81]
	v_mfma_f32_16x16x32_bf16 v[74:77], v[190:193], v[214:217], v[74:77]
	v_mfma_f32_16x16x32_bf16 v[70:73], v[176:179], v[222:225], v[70:73]
	v_mfma_f32_16x16x32_bf16 v[66:69], v[190:193], v[222:225], v[66:69]
	v_mfma_f32_16x16x32_bf16 v[110:113], v[180:183], v[202:205], v[110:113]
	v_mfma_f32_16x16x32_bf16 v[106:109], v[194:197], v[202:205], v[106:109]
	v_mfma_f32_16x16x32_bf16 v[94:97], v[180:183], v[210:213], v[94:97]
	v_mfma_f32_16x16x32_bf16 v[90:93], v[194:197], v[210:213], v[90:93]
	v_mfma_f32_16x16x32_bf16 v[78:81], v[180:183], v[218:221], v[78:81]
	v_mfma_f32_16x16x32_bf16 v[74:77], v[194:197], v[218:221], v[74:77]
	v_mfma_f32_16x16x32_bf16 v[70:73], v[180:183], v[226:229], v[70:73]
	v_mfma_f32_16x16x32_bf16 v[66:69], v[194:197], v[226:229], v[66:69]
	s_setprio 0
	s_barrier
	s_add_i32 s72, s72, s40
	v_lshl_add_u64 v[162:163], s[22:23], 0, v[134:135]
	s_mov_b32 m0, s72
	ds_read_b128 v[198:201], v145 offset:16384
	ds_read_b128 v[202:205], v145 offset:17408
	ds_read_b128 v[206:209], v145 offset:18432
	ds_read_b128 v[210:213], v145 offset:19456
	ds_read_b128 v[214:217], v145 offset:20480
	ds_read_b128 v[218:221], v145 offset:21504
	ds_read_b128 v[222:225], v145 offset:22528
	ds_read_b128 v[226:229], v145 offset:23552
	global_load_lds_dwordx4 v[162:163], off
	s_add_i32 m0, s72, 0x2000
	s_add_u32 s72, s22, 0x40000
	v_lshl_add_u64 v[230:231], s[22:23], 0, v[130:131]
	s_addc_u32 s73, s23, 0
	s_add_i32 s74, s74, s40
	global_load_lds_dwordx4 v[230:231], off
	s_mov_b32 m0, s74
	v_lshl_add_u64 v[238:239], s[38:39], 0, v[132:133]
	global_load_lds_dwordx4 v134, s[72:73]
	s_add_i32 m0, s74, 0x2000
	s_nop 0
	global_load_lds_dwordx4 v130, s[72:73]
	v_lshl_add_u64 v[236:237], s[38:39], 0, v[136:137]
	s_mov_b32 m0, s11
	s_nop 0
	global_load_lds_dwordx4 v[236:237], off
	s_mov_b32 m0, s41
	s_nop 0
	global_load_lds_dwordx4 v[238:239], off
	s_waitcnt vmcnt(8)
	s_waitcnt lgkmcnt(0)
	s_barrier
; #define PG8_STAGE(bufoff, gbase, voff) do { _Pragma("unroll") for (int _i = 0; _i < 2; ++_i) \
;         __builtin_amdgcn_global_load_lds((const unsigned*)((const char*)(gbase) + (voff)[_i]), (LAS unsigned*)(lds + (bufoff) + ldsw + _i * 8192), 16, 0, 0); } while (0)
; #define PG8_LDA(dst, b, h) do { _Pragma("unroll") for (int m = 0; m < 4; ++m) _Pragma("unroll") for (int k = 0; k < 2; ++k) dst[m][k] = *(const LAS bf16x8*)(lds + PG8_SA(b, h) + aoff + m * 2048 + k * 1024); } while (0)
; #define PG8_LDB(dst, b, h) do { _Pragma("unroll") for (int n = 0; n < 2; ++n) _Pragma("unroll") for (int k = 0; k < 2; ++k) dst[n][k] = *(const LAS bf16x8*)(lds + PG8_SB(b, h) + boff + n * 2048 + k * 1024); } while (0)
; #define PG8_MMA(ai, bj, At, Bt) do { __builtin_amdgcn_s_setprio(1); _Pragma("unroll") for (int m = 0; m < 4; ++m) _Pragma("unroll") for (int n = 0; n < 2; ++n) _Pragma("unroll") for (int k = 0; k < 2; ++k) \
;         acc[ai][bj][m][n] = __builtin_amdgcn_mfma_f32_16x16x32_bf16(Bt[n][k], At[m][k], acc[ai][bj][m][n], 0, 0, 0); __builtin_amdgcn_s_setprio(0); } while (0)
; #define PG8_WAIT_V(n) asm volatile("s_waitcnt vmcnt(" #n ")" ::: "memory")
; #define PG8_WAIT_L(n) asm volatile("s_waitcnt lgkmcnt(" #n ")" ::: "memory")
; #define PG8_BAR __builtin_amdgcn_s_barrier()
; #define PG8_SCHED __builtin_amdgcn_sched_barrier(0)
; template <class Epi>
; DI void gemm_phase(int wid0, LAS unsigned char* lds, const Gemm g, const StaticOrder& S, const Epi& E) {
;     ...
;             PG8_WAIT_V(8); PG8_WAIT_L(0); PG8_BAR; PG8_MMA(1, 0, At, B0); PG8_MMA(1, 1, At, B1); PG8_BAR; PG8_SCHED;
;             PG8_LDB(B0, 1, 0); PG8_LDB(B1, 1, 1); PG8_SCHED; PG8_LDA(At, 1, 0); PG8_STAGE(PG8_SA(0, 1), a2 + hstep, voffA);
;             PG8_WAIT_V(8); PG8_WAIT_L(0); PG8_BAR; PG8_MMA(0, 0, At, B0); PG8_MMA(0, 1, At, B1); PG8_BAR; PG8_SCHED;
	s_setprio 1
	s_waitcnt lgkmcnt(0)
	v_mfma_f32_16x16x32_bf16 v[62:65], v[146:149], v[198:201], v[62:65]
	v_mfma_f32_16x16x32_bf16 v[58:61], v[154:157], v[198:201], v[58:61]
	v_mfma_f32_16x16x32_bf16 v[54:57], v[146:149], v[206:209], v[54:57]
	v_mfma_f32_16x16x32_bf16 v[50:53], v[154:157], v[206:209], v[50:53]
	v_mfma_f32_16x16x32_bf16 v[38:41], v[146:149], v[214:217], v[38:41]
	v_mfma_f32_16x16x32_bf16 v[34:37], v[154:157], v[214:217], v[34:37]
	v_mfma_f32_16x16x32_bf16 v[22:25], v[146:149], v[222:225], v[22:25]
	v_mfma_f32_16x16x32_bf16 v[18:21], v[154:157], v[222:225], v[18:21]
	v_mfma_f32_16x16x32_bf16 v[62:65], v[150:153], v[202:205], v[62:65]
	v_mfma_f32_16x16x32_bf16 v[58:61], v[158:161], v[202:205], v[58:61]
	v_mfma_f32_16x16x32_bf16 v[54:57], v[150:153], v[210:213], v[54:57]
	v_mfma_f32_16x16x32_bf16 v[50:53], v[158:161], v[210:213], v[50:53]
	v_mfma_f32_16x16x32_bf16 v[38:41], v[150:153], v[218:221], v[38:41]
	v_mfma_f32_16x16x32_bf16 v[34:37], v[158:161], v[218:221], v[34:37]
	v_mfma_f32_16x16x32_bf16 v[22:25], v[150:153], v[226:229], v[22:25]
	v_mfma_f32_16x16x32_bf16 v[18:21], v[158:161], v[226:229], v[18:21]
	v_mfma_f32_16x16x32_bf16 v[46:49], v[176:179], v[198:201], v[46:49]
	v_mfma_f32_16x16x32_bf16 v[42:45], v[190:193], v[198:201], v[42:45]
	v_mfma_f32_16x16x32_bf16 v[30:33], v[176:179], v[206:209], v[30:33]
	v_mfma_f32_16x16x32_bf16 v[26:29], v[190:193], v[206:209], v[26:29]
	v_mfma_f32_16x16x32_bf16 v[14:17], v[176:179], v[214:217], v[14:17]
	v_mfma_f32_16x16x32_bf16 v[10:13], v[190:193], v[214:217], v[10:13]
	v_mfma_f32_16x16x32_bf16 v[6:9], v[176:179], v[222:225], v[6:9]
	v_mfma_f32_16x16x32_bf16 v[2:5], v[190:193], v[222:225], v[2:5]
	v_mfma_f32_16x16x32_bf16 v[46:49], v[180:183], v[202:205], v[46:49]
	v_mfma_f32_16x16x32_bf16 v[42:45], v[194:197], v[202:205], v[42:45]
	v_mfma_f32_16x16x32_bf16 v[30:33], v[180:183], v[210:213], v[30:33]
	v_mfma_f32_16x16x32_bf16 v[26:29], v[194:197], v[210:213], v[26:29]
	v_mfma_f32_16x16x32_bf16 v[14:17], v[180:183], v[218:221], v[14:17]
	v_mfma_f32_16x16x32_bf16 v[10:13], v[194:197], v[218:221], v[10:13]
	v_mfma_f32_16x16x32_bf16 v[6:9], v[180:183], v[226:229], v[6:9]
	v_mfma_f32_16x16x32_bf16 v[2:5], v[194:197], v[226:229], v[2:5]
	s_setprio 0
	s_barrier
	s_add_i32 s72, 0, 0x18000
	v_add_u32_e32 v0, s72, v143
	s_add_i32 s73, 0, 0x1c000
	ds_read_b128 v[146:149], v0
	ds_read_b128 v[150:153], v0 offset:1024
	ds_read_b128 v[154:157], v0 offset:2048
	ds_read_b128 v[158:161], v0 offset:3072
	v_add_u32_e32 v0, s73, v143
	ds_read_b128 v[176:179], v0
	ds_read_b128 v[180:183], v0 offset:1024
	ds_read_b128 v[190:193], v0 offset:2048
	ds_read_b128 v[194:197], v0 offset:3072
	s_add_u32 s38, s38, 0x40000
	s_addc_u32 s39, s39, 0
	s_mov_b32 m0, s46
	ds_read_b128 v[198:201], v145 offset:32768
	ds_read_b128 v[202:205], v145 offset:33792
	ds_read_b128 v[206:209], v145 offset:34816
	ds_read_b128 v[210:213], v145 offset:35840
	ds_read_b128 v[214:217], v145 offset:36864
	ds_read_b128 v[218:221], v145 offset:37888
	ds_read_b128 v[222:225], v145 offset:38912
	ds_read_b128 v[226:229], v145 offset:39936
	global_load_lds_dwordx4 v136, s[38:39]
	v_lshl_add_u64 v[240:241], s[38:39], 0, v[132:133]
	s_mov_b32 m0, s47
	s_nop 0
	global_load_lds_dwordx4 v[240:241], off
	s_waitcnt vmcnt(8)
	s_waitcnt lgkmcnt(0)
	s_barrier
	s_setprio 1
	s_waitcnt lgkmcnt(0)
	v_mfma_f32_16x16x32_bf16 v[126:129], v[146:149], v[198:201], v[126:129]
	v_mfma_f32_16x16x32_bf16 v[122:125], v[154:157], v[198:201], v[122:125]
	v_mfma_f32_16x16x32_bf16 v[118:121], v[146:149], v[206:209], v[118:121]
	v_mfma_f32_16x16x32_bf16 v[114:117], v[154:157], v[206:209], v[114:117]
	v_mfma_f32_16x16x32_bf16 v[102:105], v[146:149], v[214:217], v[102:105]
	v_mfma_f32_16x16x32_bf16 v[98:101], v[154:157], v[214:217], v[98:101]
	v_mfma_f32_16x16x32_bf16 v[86:89], v[146:149], v[222:225], v[86:89]
	v_mfma_f32_16x16x32_bf16 v[82:85], v[154:157], v[222:225], v[82:85]
	v_mfma_f32_16x16x32_bf16 v[126:129], v[150:153], v[202:205], v[126:129]
	v_mfma_f32_16x16x32_bf16 v[122:125], v[158:161], v[202:205], v[122:125]
	v_mfma_f32_16x16x32_bf16 v[118:121], v[150:153], v[210:213], v[118:121]
	v_mfma_f32_16x16x32_bf16 v[114:117], v[158:161], v[210:213], v[114:117]
	v_mfma_f32_16x16x32_bf16 v[102:105], v[150:153], v[218:221], v[102:105]
	v_mfma_f32_16x16x32_bf16 v[98:101], v[158:161], v[218:221], v[98:101]
	v_mfma_f32_16x16x32_bf16 v[86:89], v[150:153], v[226:229], v[86:89]
	v_mfma_f32_16x16x32_bf16 v[82:85], v[158:161], v[226:229], v[82:85]
	v_mfma_f32_16x16x32_bf16 v[110:113], v[176:179], v[198:201], v[110:113]
	v_mfma_f32_16x16x32_bf16 v[106:109], v[190:193], v[198:201], v[106:109]
	v_mfma_f32_16x16x32_bf16 v[94:97], v[176:179], v[206:209], v[94:97]
	v_mfma_f32_16x16x32_bf16 v[90:93], v[190:193], v[206:209], v[90:93]
	v_mfma_f32_16x16x32_bf16 v[78:81], v[176:179], v[214:217], v[78:81]
	v_mfma_f32_16x16x32_bf16 v[74:77], v[190:193], v[214:217], v[74:77]
	v_mfma_f32_16x16x32_bf16 v[70:73], v[176:179], v[222:225], v[70:73]
	v_mfma_f32_16x16x32_bf16 v[66:69], v[190:193], v[222:225], v[66:69]
	v_mfma_f32_16x16x32_bf16 v[110:113], v[180:183], v[202:205], v[110:113]
	v_mfma_f32_16x16x32_bf16 v[106:109], v[194:197], v[202:205], v[106:109]
	v_mfma_f32_16x16x32_bf16 v[94:97], v[180:183], v[210:213], v[94:97]
	v_mfma_f32_16x16x32_bf16 v[90:93], v[194:197], v[210:213], v[90:93]
	v_mfma_f32_16x16x32_bf16 v[78:81], v[180:183], v[218:221], v[78:81]
	v_mfma_f32_16x16x32_bf16 v[74:77], v[194:197], v[218:221], v[74:77]
	v_mfma_f32_16x16x32_bf16 v[70:73], v[180:183], v[226:229], v[70:73]
	v_mfma_f32_16x16x32_bf16 v[66:69], v[194:197], v[226:229], v[66:69]
	s_setprio 0
	s_barrier
; #define PG8_STAGE(bufoff, gbase, voff) do { _Pragma("unroll") for (int _i = 0; _i < 2; ++_i) \
;         __builtin_amdgcn_global_load_lds((const unsigned*)((const char*)(gbase) + (voff)[_i]), (LAS unsigned*)(lds + (bufoff) + ldsw + _i * 8192), 16, 0, 0); } while (0)
; #define PG8_LDA(dst, b, h) do { _Pragma("unroll") for (int m = 0; m < 4; ++m) _Pragma("unroll") for (int k = 0; k < 2; ++k) dst[m][k] = *(const LAS bf16x8*)(lds + PG8_SA(b, h) + aoff + m * 2048 + k * 1024); } while (0)
; #define PG8_MMA(ai, bj, At, Bt) do { __builtin_amdgcn_s_setprio(1); _Pragma("unroll") for (int m = 0; m < 4; ++m) _Pragma("unroll") for (int n = 0; n < 2; ++n) _Pragma("unroll") for (int k = 0; k < 2; ++k) \
;         acc[ai][bj][m][n] = __builtin_amdgcn_mfma_f32_16x16x32_bf16(Bt[n][k], At[m][k], acc[ai][bj][m][n], 0, 0, 0); __builtin_amdgcn_s_setprio(0); } while (0)
; #define PG8_WAIT_V(n) asm volatile("s_waitcnt vmcnt(" #n ")" ::: "memory")
; #define PG8_WAIT_L(n) asm volatile("s_waitcnt lgkmcnt(" #n ")" ::: "memory")
; #define PG8_BAR __builtin_amdgcn_s_barrier()
; #define PG8_SCHED __builtin_amdgcn_sched_barrier(0)
; template <class Epi>
; DI void gemm_phase(int wid0, LAS unsigned char* lds, const Gemm g, const StaticOrder& S, const Epi& E) {
;     ...
;             PG8_LDA(At, 1, 1); PG8_STAGE(PG8_SB(1, 0), b3, voffB); PG8_STAGE(PG8_SB(1, 1), b3 + hstep, voffB); PG8_STAGE(PG8_SA(1, 0), a3, voffA);
;             PG8_WAIT_V(8); PG8_WAIT_L(0); PG8_BAR; PG8_MMA(1, 0, At, B0); PG8_MMA(1, 1, At, B1); PG8_BAR; PG8_SCHED;
;         }
	s_add_i32 s38, s72, s40
	v_lshl_add_u64 v[162:163], v[162:163], 0, s[30:31]
	s_mov_b32 m0, s38
	ds_read_b128 v[198:201], v145 offset:49152
	ds_read_b128 v[202:205], v145 offset:50176
	ds_read_b128 v[206:209], v145 offset:51200
	ds_read_b128 v[210:213], v145 offset:52224
	ds_read_b128 v[214:217], v145 offset:53248
	ds_read_b128 v[218:221], v145 offset:54272
	ds_read_b128 v[222:225], v145 offset:55296
	ds_read_b128 v[226:229], v145 offset:56320
	global_load_lds_dwordx4 v[162:163], off
	s_add_i32 m0, s38, 0x2000
	s_add_u32 s22, s22, 0x40080
	v_lshl_add_u64 v[162:163], v[230:231], 0, s[30:31]
	s_addc_u32 s23, s23, 0
	s_add_i32 s38, s73, s40
	global_load_lds_dwordx4 v[162:163], off
	s_mov_b32 m0, s38
	s_nop 0
	global_load_lds_dwordx4 v134, s[22:23]
	s_add_i32 m0, s38, 0x2000
	s_nop 0
	global_load_lds_dwordx4 v130, s[22:23]
	v_lshl_add_u64 v[162:163], v[236:237], 0, s[30:31]
	s_mov_b32 m0, s2
	s_nop 0
	global_load_lds_dwordx4 v[162:163], off
	v_lshl_add_u64 v[162:163], v[238:239], 0, s[30:31]
	s_mov_b32 m0, s48
	s_nop 0
	global_load_lds_dwordx4 v[162:163], off
	s_waitcnt vmcnt(8)
	s_waitcnt lgkmcnt(0)
	s_barrier
	s_setprio 1
	s_waitcnt lgkmcnt(0)
	v_mfma_f32_16x16x32_bf16 v[62:65], v[146:149], v[198:201], v[62:65]
	v_mfma_f32_16x16x32_bf16 v[58:61], v[154:157], v[198:201], v[58:61]
	v_mfma_f32_16x16x32_bf16 v[54:57], v[146:149], v[206:209], v[54:57]
	v_mfma_f32_16x16x32_bf16 v[50:53], v[154:157], v[206:209], v[50:53]
	v_mfma_f32_16x16x32_bf16 v[38:41], v[146:149], v[214:217], v[38:41]
	v_mfma_f32_16x16x32_bf16 v[34:37], v[154:157], v[214:217], v[34:37]
	v_mfma_f32_16x16x32_bf16 v[22:25], v[146:149], v[222:225], v[22:25]
	v_mfma_f32_16x16x32_bf16 v[18:21], v[154:157], v[222:225], v[18:21]
	v_mfma_f32_16x16x32_bf16 v[62:65], v[150:153], v[202:205], v[62:65]
	v_mfma_f32_16x16x32_bf16 v[58:61], v[158:161], v[202:205], v[58:61]
	v_mfma_f32_16x16x32_bf16 v[54:57], v[150:153], v[210:213], v[54:57]
	v_mfma_f32_16x16x32_bf16 v[50:53], v[158:161], v[210:213], v[50:53]
	v_mfma_f32_16x16x32_bf16 v[38:41], v[150:153], v[218:221], v[38:41]
	v_mfma_f32_16x16x32_bf16 v[34:37], v[158:161], v[218:221], v[34:37]
	v_mfma_f32_16x16x32_bf16 v[22:25], v[150:153], v[226:229], v[22:25]
	v_mfma_f32_16x16x32_bf16 v[18:21], v[158:161], v[226:229], v[18:21]
	v_mfma_f32_16x16x32_bf16 v[46:49], v[176:179], v[198:201], v[46:49]
	v_mfma_f32_16x16x32_bf16 v[42:45], v[190:193], v[198:201], v[42:45]
	v_mfma_f32_16x16x32_bf16 v[30:33], v[176:179], v[206:209], v[30:33]
	v_mfma_f32_16x16x32_bf16 v[26:29], v[190:193], v[206:209], v[26:29]
	v_mfma_f32_16x16x32_bf16 v[14:17], v[176:179], v[214:217], v[14:17]
	v_mfma_f32_16x16x32_bf16 v[10:13], v[190:193], v[214:217], v[10:13]
	v_mfma_f32_16x16x32_bf16 v[6:9], v[176:179], v[222:225], v[6:9]
	v_mfma_f32_16x16x32_bf16 v[2:5], v[190:193], v[222:225], v[2:5]
	v_mfma_f32_16x16x32_bf16 v[46:49], v[180:183], v[202:205], v[46:49]
	v_mfma_f32_16x16x32_bf16 v[42:45], v[194:197], v[202:205], v[42:45]
	v_mfma_f32_16x16x32_bf16 v[30:33], v[180:183], v[210:213], v[30:33]
	v_mfma_f32_16x16x32_bf16 v[26:29], v[194:197], v[210:213], v[26:29]
	v_mfma_f32_16x16x32_bf16 v[14:17], v[180:183], v[218:221], v[14:17]
	v_mfma_f32_16x16x32_bf16 v[10:13], v[194:197], v[218:221], v[10:13]
	v_mfma_f32_16x16x32_bf16 v[6:9], v[180:183], v[226:229], v[6:9]
	v_mfma_f32_16x16x32_bf16 v[2:5], v[194:197], v[226:229], v[2:5]
	s_setprio 0
	s_barrier
	s_add_i32 s71, s71, 2
	s_add_u32 s20, s20, 0x100
	s_addc_u32 s21, s21, 0
	s_add_u32 s69, s69, 0x100
	s_addc_u32 s70, s70, 0
	s_cmp_gt_u32 s71, 13
	s_cbranch_scc0 .LBB0_139
	s_and_b64 vcc, exec, s[8:9]
	s_cbranch_vccz .LBB0_142
	s_barrier

; #define PG8_STAGE(bufoff, gbase, voff) do { _Pragma("unroll") for (int _i = 0; _i < 2; ++_i) \
;         __builtin_amdgcn_global_load_lds((const unsigned*)((const char*)(gbase) + (voff)[_i]), (LAS unsigned*)(lds + (bufoff) + ldsw + _i * 8192), 16, 0, 0); } while (0)
; #define PG8_LDA(dst, b, h) do { _Pragma("unroll") for (int m = 0; m < 4; ++m) _Pragma("unroll") for (int k = 0; k < 2; ++k) dst[m][k] = *(const LAS bf16x8*)(lds + PG8_SA(b, h) + aoff + m * 2048 + k * 1024); } while (0)
; #define PG8_LDB(dst, b, h) do { _Pragma("unroll") for (int n = 0; n < 2; ++n) _Pragma("unroll") for (int k = 0; k < 2; ++k) dst[n][k] = *(const LAS bf16x8*)(lds + PG8_SB(b, h) + boff + n * 2048 + k * 1024); } while (0)
; #define PG8_MMA(ai, bj, At, Bt) do { __builtin_amdgcn_s_setprio(1); _Pragma("unroll") for (int m = 0; m < 4; ++m) _Pragma("unroll") for (int n = 0; n < 2; ++n) _Pragma("unroll") for (int k = 0; k < 2; ++k) \
;         acc[ai][bj][m][n] = __builtin_amdgcn_mfma_f32_16x16x32_bf16(Bt[n][k], At[m][k], acc[ai][bj][m][n], 0, 0, 0); __builtin_amdgcn_s_setprio(0); } while (0)
; #define PG8_WAIT_V(n) asm volatile("s_waitcnt vmcnt(" #n ")" ::: "memory")
; #define PG8_WAIT_L(n) asm volatile("s_waitcnt lgkmcnt(" #n ")" ::: "memory")
; #define PG8_BAR __builtin_amdgcn_s_barrier()
; #define PG8_SCHED __builtin_amdgcn_sched_barrier(0)
; template <class Epi>
; DI void gemm_phase(int wid0, LAS unsigned char* lds, const Gemm g, const StaticOrder& S, const Epi& E) {
;     ...
;             PG8_LDB(B0, 0, 0); PG8_LDB(B1, 0, 1); PG8_SCHED; PG8_LDA(At, 0, 0); PG8_STAGE(PG8_SA(1, 1), a1 + hstep, voffA);
;             PG8_WAIT_V(8); PG8_WAIT_L(0); PG8_BAR; PG8_MMA(0, 0, At, B0); PG8_MMA(0, 1, At, B1); PG8_BAR; PG8_SCHED;
;             PG8_LDA(At, 0, 1); PG8_STAGE(PG8_SB(0, 0), b2, voffB); PG8_STAGE(PG8_SB(0, 1), b2 + hstep, voffB); PG8_STAGE(PG8_SA(0, 0), a2, voffA);
.LBB0_207:
	s_add_u32 s46, s44, 0xfff80080
	s_addc_u32 s47, s45, -1
	s_add_i32 s72, 0, 0x10000
	s_cmp_eq_u32 s71, 28
	s_cselect_b32 s49, s19, s47
	s_cselect_b32 s48, s66, s46
	v_add_u32_e32 v144, s72, v147
	s_cselect_b32 s47, s17, s70
	s_cselect_b32 s46, s67, s69
	s_add_i32 s74, 0, 0x14000
	ds_read_b128 v[140:143], v144
	ds_read_b128 v[150:153], v144 offset:1024
	ds_read_b128 v[154:157], v144 offset:2048
	ds_read_b128 v[158:161], v144 offset:3072
	v_add_u32_e32 v144, s74, v147
	ds_read_b128 v[176:179], v144
	ds_read_b128 v[180:183], v144 offset:1024
	ds_read_b128 v[190:193], v144 offset:2048
	ds_read_b128 v[194:197], v144 offset:3072
	s_add_i32 m0, s41, 0xc000
	ds_read_b128 v[198:201], v149
	ds_read_b128 v[202:205], v149 offset:1024
	ds_read_b128 v[206:209], v149 offset:2048
	ds_read_b128 v[210:213], v149 offset:3072
	ds_read_b128 v[214:217], v149 offset:4096
	ds_read_b128 v[218:221], v149 offset:5120
	ds_read_b128 v[222:225], v149 offset:6144
	ds_read_b128 v[226:229], v149 offset:7168
	global_load_lds_dwordx4 v136, s[44:45]
	s_add_i32 m0, s41, 0xe000
	s_nop 0
	global_load_lds_dwordx4 v138, s[44:45]
	s_waitcnt vmcnt(8)
	s_waitcnt lgkmcnt(0)
	s_barrier
	s_setprio 1
	s_waitcnt lgkmcnt(0)
	v_mfma_f32_16x16x32_bf16 v[126:129], v[140:143], v[198:201], v[126:129]
	v_mfma_f32_16x16x32_bf16 v[122:125], v[154:157], v[198:201], v[122:125]
	v_mfma_f32_16x16x32_bf16 v[110:113], v[140:143], v[206:209], v[110:113]
	v_mfma_f32_16x16x32_bf16 v[106:109], v[154:157], v[206:209], v[106:109]
	v_mfma_f32_16x16x32_bf16 v[94:97], v[140:143], v[214:217], v[94:97]
	v_mfma_f32_16x16x32_bf16 v[90:93], v[154:157], v[214:217], v[90:93]
	v_mfma_f32_16x16x32_bf16 v[78:81], v[140:143], v[222:225], v[78:81]
	v_mfma_f32_16x16x32_bf16 v[74:77], v[154:157], v[222:225], v[74:77]
	v_mfma_f32_16x16x32_bf16 v[126:129], v[150:153], v[202:205], v[126:129]
	v_mfma_f32_16x16x32_bf16 v[122:125], v[158:161], v[202:205], v[122:125]
	v_mfma_f32_16x16x32_bf16 v[110:113], v[150:153], v[210:213], v[110:113]
	v_mfma_f32_16x16x32_bf16 v[106:109], v[158:161], v[210:213], v[106:109]
	v_mfma_f32_16x16x32_bf16 v[94:97], v[150:153], v[218:221], v[94:97]
	v_mfma_f32_16x16x32_bf16 v[90:93], v[158:161], v[218:221], v[90:93]
	v_mfma_f32_16x16x32_bf16 v[78:81], v[150:153], v[226:229], v[78:81]
	v_mfma_f32_16x16x32_bf16 v[74:77], v[158:161], v[226:229], v[74:77]
	v_mfma_f32_16x16x32_bf16 v[118:121], v[176:179], v[198:201], v[118:121]
	v_mfma_f32_16x16x32_bf16 v[114:117], v[190:193], v[198:201], v[114:117]
	v_mfma_f32_16x16x32_bf16 v[102:105], v[176:179], v[206:209], v[102:105]
	v_mfma_f32_16x16x32_bf16 v[98:101], v[190:193], v[206:209], v[98:101]
	v_mfma_f32_16x16x32_bf16 v[86:89], v[176:179], v[214:217], v[86:89]
	v_mfma_f32_16x16x32_bf16 v[82:85], v[190:193], v[214:217], v[82:85]
	v_mfma_f32_16x16x32_bf16 v[70:73], v[176:179], v[222:225], v[70:73]
	v_mfma_f32_16x16x32_bf16 v[66:69], v[190:193], v[222:225], v[66:69]
	v_mfma_f32_16x16x32_bf16 v[118:121], v[180:183], v[202:205], v[118:121]
	v_mfma_f32_16x16x32_bf16 v[114:117], v[194:197], v[202:205], v[114:117]
	v_mfma_f32_16x16x32_bf16 v[102:105], v[180:183], v[210:213], v[102:105]
	v_mfma_f32_16x16x32_bf16 v[98:101], v[194:197], v[210:213], v[98:101]
	v_mfma_f32_16x16x32_bf16 v[86:89], v[180:183], v[218:221], v[86:89]
	v_mfma_f32_16x16x32_bf16 v[82:85], v[194:197], v[218:221], v[82:85]
	v_mfma_f32_16x16x32_bf16 v[70:73], v[180:183], v[226:229], v[70:73]
	v_mfma_f32_16x16x32_bf16 v[66:69], v[194:197], v[226:229], v[66:69]
	s_setprio 0
	s_barrier
	s_add_i32 s72, s72, s40
	v_lshl_add_u64 v[144:145], s[46:47], 0, v[0:1]
	s_mov_b32 m0, s72
	ds_read_b128 v[198:201], v149 offset:16384
	ds_read_b128 v[202:205], v149 offset:17408
	ds_read_b128 v[206:209], v149 offset:18432
	ds_read_b128 v[210:213], v149 offset:19456
	ds_read_b128 v[214:217], v149 offset:20480
	ds_read_b128 v[218:221], v149 offset:21504
	ds_read_b128 v[222:225], v149 offset:22528
	ds_read_b128 v[226:229], v149 offset:23552
	global_load_lds_dwordx4 v[144:145], off
	s_add_i32 m0, s72, 0x2000
	s_add_u32 s72, s46, 0x80000
	v_lshl_add_u64 v[162:163], s[46:47], 0, v[130:131]
	s_addc_u32 s73, s47, 0
	s_add_i32 s74, s74, s40
	global_load_lds_dwordx4 v[162:163], off
	v_lshl_add_u64 v[230:231], s[72:73], 0, v[0:1]
	s_mov_b32 m0, s74
	v_lshl_add_u64 v[236:237], s[48:49], 0, v[132:133]
	global_load_lds_dwordx4 v[230:231], off
	s_add_i32 m0, s74, 0x2000
	s_nop 0
	global_load_lds_dwordx4 v130, s[72:73]
	v_lshl_add_u64 v[230:231], s[48:49], 0, v[134:135]
	s_mov_b32 m0, s41
	s_nop 0
	global_load_lds_dwordx4 v[230:231], off
	s_mov_b32 m0, s50
	s_nop 0
	global_load_lds_dwordx4 v[236:237], off
	s_waitcnt vmcnt(8)
	s_waitcnt lgkmcnt(0)
	s_barrier
; #define PG8_STAGE(bufoff, gbase, voff) do { _Pragma("unroll") for (int _i = 0; _i < 2; ++_i) \
;         __builtin_amdgcn_global_load_lds((const unsigned*)((const char*)(gbase) + (voff)[_i]), (LAS unsigned*)(lds + (bufoff) + ldsw + _i * 8192), 16, 0, 0); } while (0)
; #define PG8_LDA(dst, b, h) do { _Pragma("unroll") for (int m = 0; m < 4; ++m) _Pragma("unroll") for (int k = 0; k < 2; ++k) dst[m][k] = *(const LAS bf16x8*)(lds + PG8_SA(b, h) + aoff + m * 2048 + k * 1024); } while (0)
; #define PG8_LDB(dst, b, h) do { _Pragma("unroll") for (int n = 0; n < 2; ++n) _Pragma("unroll") for (int k = 0; k < 2; ++k) dst[n][k] = *(const LAS bf16x8*)(lds + PG8_SB(b, h) + boff + n * 2048 + k * 1024); } while (0)
; #define PG8_MMA(ai, bj, At, Bt) do { __builtin_amdgcn_s_setprio(1); _Pragma("unroll") for (int m = 0; m < 4; ++m) _Pragma("unroll") for (int n = 0; n < 2; ++n) _Pragma("unroll") for (int k = 0; k < 2; ++k) \
;         acc[ai][bj][m][n] = __builtin_amdgcn_mfma_f32_16x16x32_bf16(Bt[n][k], At[m][k], acc[ai][bj][m][n], 0, 0, 0); __builtin_amdgcn_s_setprio(0); } while (0)
; #define PG8_WAIT_V(n) asm volatile("s_waitcnt vmcnt(" #n ")" ::: "memory")
; #define PG8_WAIT_L(n) asm volatile("s_waitcnt lgkmcnt(" #n ")" ::: "memory")
; #define PG8_BAR __builtin_amdgcn_s_barrier()
; #define PG8_SCHED __builtin_amdgcn_sched_barrier(0)
; template <class Epi>
; DI void gemm_phase(int wid0, LAS unsigned char* lds, const Gemm g, const StaticOrder& S, const Epi& E) {
;     ...
;             PG8_WAIT_V(8); PG8_WAIT_L(0); PG8_BAR; PG8_MMA(1, 0, At, B0); PG8_MMA(1, 1, At, B1); PG8_BAR; PG8_SCHED;
;             PG8_LDB(B0, 1, 0); PG8_LDB(B1, 1, 1); PG8_SCHED; PG8_LDA(At, 1, 0); PG8_STAGE(PG8_SA(0, 1), a2 + hstep, voffA);
;             PG8_WAIT_V(8); PG8_WAIT_L(0); PG8_BAR; PG8_MMA(0, 0, At, B0); PG8_MMA(0, 1, At, B1); PG8_BAR; PG8_SCHED;
	s_setprio 1
	s_waitcnt lgkmcnt(0)
	v_mfma_f32_16x16x32_bf16 v[62:65], v[140:143], v[198:201], v[62:65]
	v_mfma_f32_16x16x32_bf16 v[58:61], v[154:157], v[198:201], v[58:61]
	v_mfma_f32_16x16x32_bf16 v[46:49], v[140:143], v[206:209], v[46:49]
	v_mfma_f32_16x16x32_bf16 v[42:45], v[154:157], v[206:209], v[42:45]
	v_mfma_f32_16x16x32_bf16 v[30:33], v[140:143], v[214:217], v[30:33]
	v_mfma_f32_16x16x32_bf16 v[26:29], v[154:157], v[214:217], v[26:29]
	v_mfma_f32_16x16x32_bf16 v[14:17], v[140:143], v[222:225], v[14:17]
	v_mfma_f32_16x16x32_bf16 v[10:13], v[154:157], v[222:225], v[10:13]
	v_mfma_f32_16x16x32_bf16 v[62:65], v[150:153], v[202:205], v[62:65]
	v_mfma_f32_16x16x32_bf16 v[58:61], v[158:161], v[202:205], v[58:61]
	v_mfma_f32_16x16x32_bf16 v[46:49], v[150:153], v[210:213], v[46:49]
	v_mfma_f32_16x16x32_bf16 v[42:45], v[158:161], v[210:213], v[42:45]
	v_mfma_f32_16x16x32_bf16 v[30:33], v[150:153], v[218:221], v[30:33]
	v_mfma_f32_16x16x32_bf16 v[26:29], v[158:161], v[218:221], v[26:29]
	v_mfma_f32_16x16x32_bf16 v[14:17], v[150:153], v[226:229], v[14:17]
	v_mfma_f32_16x16x32_bf16 v[10:13], v[158:161], v[226:229], v[10:13]
	v_mfma_f32_16x16x32_bf16 v[54:57], v[176:179], v[198:201], v[54:57]
	v_mfma_f32_16x16x32_bf16 v[50:53], v[190:193], v[198:201], v[50:53]
	v_mfma_f32_16x16x32_bf16 v[38:41], v[176:179], v[206:209], v[38:41]
	v_mfma_f32_16x16x32_bf16 v[34:37], v[190:193], v[206:209], v[34:37]
	v_mfma_f32_16x16x32_bf16 v[22:25], v[176:179], v[214:217], v[22:25]
	v_mfma_f32_16x16x32_bf16 v[18:21], v[190:193], v[214:217], v[18:21]
	v_mfma_f32_16x16x32_bf16 v[6:9], v[176:179], v[222:225], v[6:9]
	v_mfma_f32_16x16x32_bf16 v[2:5], v[190:193], v[222:225], v[2:5]
	v_mfma_f32_16x16x32_bf16 v[54:57], v[180:183], v[202:205], v[54:57]
	v_mfma_f32_16x16x32_bf16 v[50:53], v[194:197], v[202:205], v[50:53]
	v_mfma_f32_16x16x32_bf16 v[38:41], v[180:183], v[210:213], v[38:41]
	v_mfma_f32_16x16x32_bf16 v[34:37], v[194:197], v[210:213], v[34:37]
	v_mfma_f32_16x16x32_bf16 v[22:25], v[180:183], v[218:221], v[22:25]
	v_mfma_f32_16x16x32_bf16 v[18:21], v[194:197], v[218:221], v[18:21]
	v_mfma_f32_16x16x32_bf16 v[6:9], v[180:183], v[226:229], v[6:9]
	v_mfma_f32_16x16x32_bf16 v[2:5], v[194:197], v[226:229], v[2:5]
	s_setprio 0
	s_barrier
	s_add_i32 s72, 0, 0x18000
	s_add_i32 s73, 0, 0x1c000
	v_add_u32_e32 v158, s72, v147
	v_add_u32_e32 v189, s73, v147
	ds_read_b128 v[140:143], v158
	ds_read_b128 v[150:153], v158 offset:1024
	ds_read_b128 v[154:157], v158 offset:2048
	ds_read_b128 v[158:161], v158 offset:3072
	ds_read_b128 v[176:179], v189
	ds_read_b128 v[180:183], v189 offset:1024
	ds_read_b128 v[190:193], v189 offset:2048
	ds_read_b128 v[194:197], v189 offset:3072
	s_add_u32 s48, s48, 0x80000
	s_addc_u32 s49, s49, 0
	s_mov_b32 m0, s51
	ds_read_b128 v[198:201], v149 offset:32768
	ds_read_b128 v[202:205], v149 offset:33792
	ds_read_b128 v[206:209], v149 offset:34816
	ds_read_b128 v[210:213], v149 offset:35840
	ds_read_b128 v[214:217], v149 offset:36864
	ds_read_b128 v[218:221], v149 offset:37888
	ds_read_b128 v[222:225], v149 offset:38912
	ds_read_b128 v[226:229], v149 offset:39936
	global_load_lds_dwordx4 v134, s[48:49]
	v_lshl_add_u64 v[238:239], s[48:49], 0, v[132:133]
	s_mov_b32 m0, s54
	s_nop 0
	global_load_lds_dwordx4 v[238:239], off
	s_waitcnt vmcnt(8)
	s_waitcnt lgkmcnt(0)
	s_barrier
	s_setprio 1
	s_waitcnt lgkmcnt(0)
	v_mfma_f32_16x16x32_bf16 v[126:129], v[140:143], v[198:201], v[126:129]
	v_mfma_f32_16x16x32_bf16 v[122:125], v[154:157], v[198:201], v[122:125]
	v_mfma_f32_16x16x32_bf16 v[110:113], v[140:143], v[206:209], v[110:113]
	v_mfma_f32_16x16x32_bf16 v[106:109], v[154:157], v[206:209], v[106:109]
	v_mfma_f32_16x16x32_bf16 v[94:97], v[140:143], v[214:217], v[94:97]
	v_mfma_f32_16x16x32_bf16 v[90:93], v[154:157], v[214:217], v[90:93]
	v_mfma_f32_16x16x32_bf16 v[78:81], v[140:143], v[222:225], v[78:81]
	v_mfma_f32_16x16x32_bf16 v[74:77], v[154:157], v[222:225], v[74:77]
	v_mfma_f32_16x16x32_bf16 v[126:129], v[150:153], v[202:205], v[126:129]
	v_mfma_f32_16x16x32_bf16 v[122:125], v[158:161], v[202:205], v[122:125]
	v_mfma_f32_16x16x32_bf16 v[110:113], v[150:153], v[210:213], v[110:113]
	v_mfma_f32_16x16x32_bf16 v[106:109], v[158:161], v[210:213], v[106:109]
	v_mfma_f32_16x16x32_bf16 v[94:97], v[150:153], v[218:221], v[94:97]
	v_mfma_f32_16x16x32_bf16 v[90:93], v[158:161], v[218:221], v[90:93]
	v_mfma_f32_16x16x32_bf16 v[78:81], v[150:153], v[226:229], v[78:81]
	v_mfma_f32_16x16x32_bf16 v[74:77], v[158:161], v[226:229], v[74:77]
	v_mfma_f32_16x16x32_bf16 v[118:121], v[176:179], v[198:201], v[118:121]
	v_mfma_f32_16x16x32_bf16 v[114:117], v[190:193], v[198:201], v[114:117]
	v_mfma_f32_16x16x32_bf16 v[102:105], v[176:179], v[206:209], v[102:105]
	v_mfma_f32_16x16x32_bf16 v[98:101], v[190:193], v[206:209], v[98:101]
	v_mfma_f32_16x16x32_bf16 v[86:89], v[176:179], v[214:217], v[86:89]
	v_mfma_f32_16x16x32_bf16 v[82:85], v[190:193], v[214:217], v[82:85]
	v_mfma_f32_16x16x32_bf16 v[70:73], v[176:179], v[222:225], v[70:73]
	v_mfma_f32_16x16x32_bf16 v[66:69], v[190:193], v[222:225], v[66:69]
	v_mfma_f32_16x16x32_bf16 v[118:121], v[180:183], v[202:205], v[118:121]
	v_mfma_f32_16x16x32_bf16 v[114:117], v[194:197], v[202:205], v[114:117]
	v_mfma_f32_16x16x32_bf16 v[102:105], v[180:183], v[210:213], v[102:105]
	v_mfma_f32_16x16x32_bf16 v[98:101], v[194:197], v[210:213], v[98:101]
	v_mfma_f32_16x16x32_bf16 v[86:89], v[180:183], v[218:221], v[86:89]
	v_mfma_f32_16x16x32_bf16 v[82:85], v[194:197], v[218:221], v[82:85]
	v_mfma_f32_16x16x32_bf16 v[70:73], v[180:183], v[226:229], v[70:73]
	v_mfma_f32_16x16x32_bf16 v[66:69], v[194:197], v[226:229], v[66:69]
	s_setprio 0
	s_barrier
; #define PG8_STAGE(bufoff, gbase, voff) do { _Pragma("unroll") for (int _i = 0; _i < 2; ++_i) \
;         __builtin_amdgcn_global_load_lds((const unsigned*)((const char*)(gbase) + (voff)[_i]), (LAS unsigned*)(lds + (bufoff) + ldsw + _i * 8192), 16, 0, 0); } while (0)
; #define PG8_LDA(dst, b, h) do { _Pragma("unroll") for (int m = 0; m < 4; ++m) _Pragma("unroll") for (int k = 0; k < 2; ++k) dst[m][k] = *(const LAS bf16x8*)(lds + PG8_SA(b, h) + aoff + m * 2048 + k * 1024); } while (0)
; #define PG8_MMA(ai, bj, At, Bt) do { __builtin_amdgcn_s_setprio(1); _Pragma("unroll") for (int m = 0; m < 4; ++m) _Pragma("unroll") for (int n = 0; n < 2; ++n) _Pragma("unroll") for (int k = 0; k < 2; ++k) \
;         acc[ai][bj][m][n] = __builtin_amdgcn_mfma_f32_16x16x32_bf16(Bt[n][k], At[m][k], acc[ai][bj][m][n], 0, 0, 0); __builtin_amdgcn_s_setprio(0); } while (0)
; #define PG8_WAIT_V(n) asm volatile("s_waitcnt vmcnt(" #n ")" ::: "memory")
; #define PG8_WAIT_L(n) asm volatile("s_waitcnt lgkmcnt(" #n ")" ::: "memory")
; #define PG8_BAR __builtin_amdgcn_s_barrier()
; #define PG8_SCHED __builtin_amdgcn_sched_barrier(0)
; template <class Epi>
; DI void gemm_phase(int wid0, LAS unsigned char* lds, const Gemm g, const StaticOrder& S, const Epi& E) {
;     ...
;             PG8_LDA(At, 1, 1); PG8_STAGE(PG8_SB(1, 0), b3, voffB); PG8_STAGE(PG8_SB(1, 1), b3 + hstep, voffB); PG8_STAGE(PG8_SA(1, 0), a3, voffA);
;             PG8_WAIT_V(8); PG8_WAIT_L(0); PG8_BAR; PG8_MMA(1, 0, At, B0); PG8_MMA(1, 1, At, B1); PG8_BAR; PG8_SCHED;
;         }
	s_add_i32 s48, s72, s40
	v_lshl_add_u64 v[144:145], v[144:145], 0, s[30:31]
	s_mov_b32 m0, s48
	ds_read_b128 v[198:201], v149 offset:49152
	ds_read_b128 v[202:205], v149 offset:50176
	ds_read_b128 v[206:209], v149 offset:51200
	ds_read_b128 v[210:213], v149 offset:52224
	ds_read_b128 v[214:217], v149 offset:53248
	ds_read_b128 v[218:221], v149 offset:54272
	ds_read_b128 v[222:225], v149 offset:55296
	ds_read_b128 v[226:229], v149 offset:56320
	global_load_lds_dwordx4 v[144:145], off
	s_add_i32 m0, s48, 0x2000
	s_add_u32 s46, s46, 0x80080
	v_lshl_add_u64 v[144:145], v[162:163], 0, s[30:31]
	s_addc_u32 s47, s47, 0
	s_add_i32 s48, s73, s40
	global_load_lds_dwordx4 v[144:145], off
	v_lshl_add_u64 v[144:145], s[46:47], 0, v[0:1]
	s_mov_b32 m0, s48
	s_nop 0
	global_load_lds_dwordx4 v[144:145], off
	s_add_i32 m0, s48, 0x2000
	s_nop 0
	global_load_lds_dwordx4 v130, s[46:47]
	v_lshl_add_u64 v[144:145], v[230:231], 0, s[30:31]
	s_mov_b32 m0, s2
	s_nop 0
	global_load_lds_dwordx4 v[144:145], off
	v_lshl_add_u64 v[144:145], v[236:237], 0, s[30:31]
	s_mov_b32 m0, s55
	s_nop 0
	global_load_lds_dwordx4 v[144:145], off
	s_waitcnt vmcnt(8)
	s_waitcnt lgkmcnt(0)
	s_barrier
	s_setprio 1
	s_waitcnt lgkmcnt(0)
	v_mfma_f32_16x16x32_bf16 v[62:65], v[140:143], v[198:201], v[62:65]
	v_mfma_f32_16x16x32_bf16 v[58:61], v[154:157], v[198:201], v[58:61]
	v_mfma_f32_16x16x32_bf16 v[46:49], v[140:143], v[206:209], v[46:49]
	v_mfma_f32_16x16x32_bf16 v[42:45], v[154:157], v[206:209], v[42:45]
	v_mfma_f32_16x16x32_bf16 v[30:33], v[140:143], v[214:217], v[30:33]
	v_mfma_f32_16x16x32_bf16 v[26:29], v[154:157], v[214:217], v[26:29]
	v_mfma_f32_16x16x32_bf16 v[14:17], v[140:143], v[222:225], v[14:17]
	v_mfma_f32_16x16x32_bf16 v[10:13], v[154:157], v[222:225], v[10:13]
	v_mfma_f32_16x16x32_bf16 v[62:65], v[150:153], v[202:205], v[62:65]
	v_mfma_f32_16x16x32_bf16 v[58:61], v[158:161], v[202:205], v[58:61]
	v_mfma_f32_16x16x32_bf16 v[46:49], v[150:153], v[210:213], v[46:49]
	v_mfma_f32_16x16x32_bf16 v[42:45], v[158:161], v[210:213], v[42:45]
	v_mfma_f32_16x16x32_bf16 v[30:33], v[150:153], v[218:221], v[30:33]
	v_mfma_f32_16x16x32_bf16 v[26:29], v[158:161], v[218:221], v[26:29]
	v_mfma_f32_16x16x32_bf16 v[14:17], v[150:153], v[226:229], v[14:17]
	v_mfma_f32_16x16x32_bf16 v[10:13], v[158:161], v[226:229], v[10:13]
	v_mfma_f32_16x16x32_bf16 v[54:57], v[176:179], v[198:201], v[54:57]
	v_mfma_f32_16x16x32_bf16 v[50:53], v[190:193], v[198:201], v[50:53]
	v_mfma_f32_16x16x32_bf16 v[38:41], v[176:179], v[206:209], v[38:41]
	v_mfma_f32_16x16x32_bf16 v[34:37], v[190:193], v[206:209], v[34:37]
	v_mfma_f32_16x16x32_bf16 v[22:25], v[176:179], v[214:217], v[22:25]
	v_mfma_f32_16x16x32_bf16 v[18:21], v[190:193], v[214:217], v[18:21]
	v_mfma_f32_16x16x32_bf16 v[6:9], v[176:179], v[222:225], v[6:9]
	v_mfma_f32_16x16x32_bf16 v[2:5], v[190:193], v[222:225], v[2:5]
	v_mfma_f32_16x16x32_bf16 v[54:57], v[180:183], v[202:205], v[54:57]
	v_mfma_f32_16x16x32_bf16 v[50:53], v[194:197], v[202:205], v[50:53]
	v_mfma_f32_16x16x32_bf16 v[38:41], v[180:183], v[210:213], v[38:41]
	v_mfma_f32_16x16x32_bf16 v[34:37], v[194:197], v[210:213], v[34:37]
	v_mfma_f32_16x16x32_bf16 v[22:25], v[180:183], v[218:221], v[22:25]
	v_mfma_f32_16x16x32_bf16 v[18:21], v[194:197], v[218:221], v[18:21]
	v_mfma_f32_16x16x32_bf16 v[6:9], v[180:183], v[226:229], v[6:9]
	v_mfma_f32_16x16x32_bf16 v[2:5], v[194:197], v[226:229], v[2:5]
	s_setprio 0
	s_barrier
	s_add_i32 s71, s71, 2
	s_add_u32 s44, s44, 0x100
	s_addc_u32 s45, s45, 0
	s_add_u32 s69, s69, 0x100
	s_addc_u32 s70, s70, 0
	s_cmp_gt_u32 s71, 29
	s_cbranch_scc0 .LBB0_207
	s_and_b64 vcc, exec, s[14:15]
	s_cbranch_vccz .LBB0_210
	s_barrier

; #define PG8_STAGE(bufoff, gbase, voff) do { _Pragma("unroll") for (int _i = 0; _i < 2; ++_i) \
;         __builtin_amdgcn_global_load_lds((const unsigned*)((const char*)(gbase) + (voff)[_i]), (LAS unsigned*)(lds + (bufoff) + ldsw + _i * 8192), 16, 0, 0); } while (0)
; #define PG8_LDA(dst, b, h) do { _Pragma("unroll") for (int m = 0; m < 4; ++m) _Pragma("unroll") for (int k = 0; k < 2; ++k) dst[m][k] = *(const LAS bf16x8*)(lds + PG8_SA(b, h) + aoff + m * 2048 + k * 1024); } while (0)
; #define PG8_LDB(dst, b, h) do { _Pragma("unroll") for (int n = 0; n < 2; ++n) _Pragma("unroll") for (int k = 0; k < 2; ++k) dst[n][k] = *(const LAS bf16x8*)(lds + PG8_SB(b, h) + boff + n * 2048 + k * 1024); } while (0)
; #define PG8_MMA(ai, bj, At, Bt) do { __builtin_amdgcn_s_setprio(1); _Pragma("unroll") for (int m = 0; m < 4; ++m) _Pragma("unroll") for (int n = 0; n < 2; ++n) _Pragma("unroll") for (int k = 0; k < 2; ++k) \
;         acc[ai][bj][m][n] = __builtin_amdgcn_mfma_f32_16x16x32_bf16(Bt[n][k], At[m][k], acc[ai][bj][m][n], 0, 0, 0); __builtin_amdgcn_s_setprio(0); } while (0)
; #define PG8_WAIT_V(n) asm volatile("s_waitcnt vmcnt(" #n ")" ::: "memory")
; #define PG8_WAIT_L(n) asm volatile("s_waitcnt lgkmcnt(" #n ")" ::: "memory")
; #define PG8_BAR __builtin_amdgcn_s_barrier()
; #define PG8_SCHED __builtin_amdgcn_sched_barrier(0)
; template <class Epi>
; DI void gemm_phase(int wid0, LAS unsigned char* lds, const Gemm g, const StaticOrder& S, const Epi& E) {
;     ...
;             PG8_LDB(B0, 0, 0); PG8_LDB(B1, 0, 1); PG8_SCHED; PG8_LDA(At, 0, 0); PG8_STAGE(PG8_SA(1, 1), a1 + hstep, voffA);
;             PG8_WAIT_V(8); PG8_WAIT_L(0); PG8_BAR; PG8_MMA(0, 0, At, B0); PG8_MMA(0, 1, At, B1); PG8_BAR; PG8_SCHED;
;             PG8_LDA(At, 0, 1); PG8_STAGE(PG8_SB(0, 0), b2, voffB); PG8_STAGE(PG8_SB(0, 1), b2 + hstep, voffB); PG8_STAGE(PG8_SA(0, 0), a2, voffA);
.LBB0_277:
	s_add_u32 s38, s28, 0xfffc0080
	s_addc_u32 s39, s29, -1
	s_add_i32 s54, 0, 0x10000
	s_cmp_eq_u32 s51, 12
	s_cselect_b32 s41, s7, s39
	s_cselect_b32 s40, s9, s38
	v_add_u32_e32 v0, s54, v153
	s_cselect_b32 s39, s10, s19
	s_cselect_b32 s38, s11, s17
	s_add_i32 s56, 0, 0x14000
	ds_read_b128 v[142:145], v0
	ds_read_b128 v[146:149], v0 offset:1024
	ds_read_b128 v[156:159], v0 offset:2048
	ds_read_b128 v[160:163], v0 offset:3072
	v_add_u32_e32 v0, s56, v153
	ds_read_b128 v[176:179], v0
	ds_read_b128 v[180:183], v0 offset:1024
	ds_read_b128 v[190:193], v0 offset:2048
	ds_read_b128 v[194:197], v0 offset:3072
	s_add_i32 m0, s44, 0xc000
	ds_read_b128 v[198:201], v155
	ds_read_b128 v[202:205], v155 offset:1024
	ds_read_b128 v[206:209], v155 offset:2048
	ds_read_b128 v[210:213], v155 offset:3072
	ds_read_b128 v[214:217], v155 offset:4096
	ds_read_b128 v[218:221], v155 offset:5120
	ds_read_b128 v[222:225], v155 offset:6144
	ds_read_b128 v[226:229], v155 offset:7168
	global_load_lds_dwordx4 v138, s[28:29]
	s_add_i32 m0, s44, 0xe000
	s_nop 0
	global_load_lds_dwordx4 v140, s[28:29]
	s_waitcnt vmcnt(8)
	s_waitcnt lgkmcnt(0)
	s_barrier
	s_setprio 1
	s_waitcnt lgkmcnt(0)
	v_mfma_f32_16x16x32_bf16 v[126:129], v[142:145], v[198:201], v[126:129]
	v_mfma_f32_16x16x32_bf16 v[122:125], v[156:159], v[198:201], v[122:125]
	v_mfma_f32_16x16x32_bf16 v[110:113], v[142:145], v[206:209], v[110:113]
	v_mfma_f32_16x16x32_bf16 v[106:109], v[156:159], v[206:209], v[106:109]
	v_mfma_f32_16x16x32_bf16 v[94:97], v[142:145], v[214:217], v[94:97]
	v_mfma_f32_16x16x32_bf16 v[90:93], v[156:159], v[214:217], v[90:93]
	v_mfma_f32_16x16x32_bf16 v[78:81], v[142:145], v[222:225], v[78:81]
	v_mfma_f32_16x16x32_bf16 v[74:77], v[156:159], v[222:225], v[74:77]
	v_mfma_f32_16x16x32_bf16 v[126:129], v[146:149], v[202:205], v[126:129]
	v_mfma_f32_16x16x32_bf16 v[122:125], v[160:163], v[202:205], v[122:125]
	v_mfma_f32_16x16x32_bf16 v[110:113], v[146:149], v[210:213], v[110:113]
	v_mfma_f32_16x16x32_bf16 v[106:109], v[160:163], v[210:213], v[106:109]
	v_mfma_f32_16x16x32_bf16 v[94:97], v[146:149], v[218:221], v[94:97]
	v_mfma_f32_16x16x32_bf16 v[90:93], v[160:163], v[218:221], v[90:93]
	v_mfma_f32_16x16x32_bf16 v[78:81], v[146:149], v[226:229], v[78:81]
	v_mfma_f32_16x16x32_bf16 v[74:77], v[160:163], v[226:229], v[74:77]
	v_mfma_f32_16x16x32_bf16 v[118:121], v[176:179], v[198:201], v[118:121]
	v_mfma_f32_16x16x32_bf16 v[114:117], v[190:193], v[198:201], v[114:117]
	v_mfma_f32_16x16x32_bf16 v[102:105], v[176:179], v[206:209], v[102:105]
	v_mfma_f32_16x16x32_bf16 v[98:101], v[190:193], v[206:209], v[98:101]
	v_mfma_f32_16x16x32_bf16 v[86:89], v[176:179], v[214:217], v[86:89]
	v_mfma_f32_16x16x32_bf16 v[82:85], v[190:193], v[214:217], v[82:85]
	v_mfma_f32_16x16x32_bf16 v[70:73], v[176:179], v[222:225], v[70:73]
	v_mfma_f32_16x16x32_bf16 v[66:69], v[190:193], v[222:225], v[66:69]
	v_mfma_f32_16x16x32_bf16 v[118:121], v[180:183], v[202:205], v[118:121]
	v_mfma_f32_16x16x32_bf16 v[114:117], v[194:197], v[202:205], v[114:117]
	v_mfma_f32_16x16x32_bf16 v[102:105], v[180:183], v[210:213], v[102:105]
	v_mfma_f32_16x16x32_bf16 v[98:101], v[194:197], v[210:213], v[98:101]
	v_mfma_f32_16x16x32_bf16 v[86:89], v[180:183], v[218:221], v[86:89]
	v_mfma_f32_16x16x32_bf16 v[82:85], v[194:197], v[218:221], v[82:85]
	v_mfma_f32_16x16x32_bf16 v[70:73], v[180:183], v[226:229], v[70:73]
	v_mfma_f32_16x16x32_bf16 v[66:69], v[194:197], v[226:229], v[66:69]
	s_setprio 0
	s_barrier
	s_add_i32 s54, s54, s2
	v_lshl_add_u64 v[150:151], s[38:39], 0, v[132:133]
	s_mov_b32 m0, s54
	ds_read_b128 v[198:201], v155 offset:16384
	ds_read_b128 v[202:205], v155 offset:17408
	ds_read_b128 v[206:209], v155 offset:18432
	ds_read_b128 v[210:213], v155 offset:19456
	ds_read_b128 v[214:217], v155 offset:20480
	ds_read_b128 v[218:221], v155 offset:21504
	ds_read_b128 v[222:225], v155 offset:22528
	ds_read_b128 v[226:229], v155 offset:23552
	global_load_lds_dwordx4 v[150:151], off
	s_add_i32 m0, s54, 0x2000
	s_add_u32 s54, s38, 0x40000
	v_lshl_add_u64 v[230:231], s[38:39], 0, v[136:137]
	s_addc_u32 s55, s39, 0
	s_add_i32 s56, s56, s2
	global_load_lds_dwordx4 v[230:231], off
	s_mov_b32 m0, s56
	v_lshl_add_u64 v[238:239], s[40:41], 0, v[134:135]
	global_load_lds_dwordx4 v132, s[54:55]
	s_add_i32 m0, s56, 0x2000
	s_nop 0
	global_load_lds_dwordx4 v136, s[54:55]
	v_lshl_add_u64 v[236:237], s[40:41], 0, v[130:131]
	s_mov_b32 m0, s44
	s_nop 0
	global_load_lds_dwordx4 v[236:237], off
	s_mov_b32 m0, s45
	s_nop 0
	global_load_lds_dwordx4 v[238:239], off
	s_waitcnt vmcnt(8)
	s_waitcnt lgkmcnt(0)
	s_barrier
; #define PG8_STAGE(bufoff, gbase, voff) do { _Pragma("unroll") for (int _i = 0; _i < 2; ++_i) \
;         __builtin_amdgcn_global_load_lds((const unsigned*)((const char*)(gbase) + (voff)[_i]), (LAS unsigned*)(lds + (bufoff) + ldsw + _i * 8192), 16, 0, 0); } while (0)
; #define PG8_LDA(dst, b, h) do { _Pragma("unroll") for (int m = 0; m < 4; ++m) _Pragma("unroll") for (int k = 0; k < 2; ++k) dst[m][k] = *(const LAS bf16x8*)(lds + PG8_SA(b, h) + aoff + m * 2048 + k * 1024); } while (0)
; #define PG8_LDB(dst, b, h) do { _Pragma("unroll") for (int n = 0; n < 2; ++n) _Pragma("unroll") for (int k = 0; k < 2; ++k) dst[n][k] = *(const LAS bf16x8*)(lds + PG8_SB(b, h) + boff + n * 2048 + k * 1024); } while (0)
; #define PG8_MMA(ai, bj, At, Bt) do { __builtin_amdgcn_s_setprio(1); _Pragma("unroll") for (int m = 0; m < 4; ++m) _Pragma("unroll") for (int n = 0; n < 2; ++n) _Pragma("unroll") for (int k = 0; k < 2; ++k) \
;         acc[ai][bj][m][n] = __builtin_amdgcn_mfma_f32_16x16x32_bf16(Bt[n][k], At[m][k], acc[ai][bj][m][n], 0, 0, 0); __builtin_amdgcn_s_setprio(0); } while (0)
; #define PG8_WAIT_V(n) asm volatile("s_waitcnt vmcnt(" #n ")" ::: "memory")
; #define PG8_WAIT_L(n) asm volatile("s_waitcnt lgkmcnt(" #n ")" ::: "memory")
; #define PG8_BAR __builtin_amdgcn_s_barrier()
; #define PG8_SCHED __builtin_amdgcn_sched_barrier(0)
; template <class Epi>
; DI void gemm_phase(int wid0, LAS unsigned char* lds, const Gemm g, const StaticOrder& S, const Epi& E) {
;     ...
;             PG8_WAIT_V(8); PG8_WAIT_L(0); PG8_BAR; PG8_MMA(1, 0, At, B0); PG8_MMA(1, 1, At, B1); PG8_BAR; PG8_SCHED;
;             PG8_LDB(B0, 1, 0); PG8_LDB(B1, 1, 1); PG8_SCHED; PG8_LDA(At, 1, 0); PG8_STAGE(PG8_SA(0, 1), a2 + hstep, voffA);
;             PG8_WAIT_V(8); PG8_WAIT_L(0); PG8_BAR; PG8_MMA(0, 0, At, B0); PG8_MMA(0, 1, At, B1); PG8_BAR; PG8_SCHED;
	s_setprio 1
	s_waitcnt lgkmcnt(0)
	v_mfma_f32_16x16x32_bf16 v[62:65], v[142:145], v[198:201], v[62:65]
	v_mfma_f32_16x16x32_bf16 v[58:61], v[156:159], v[198:201], v[58:61]
	v_mfma_f32_16x16x32_bf16 v[46:49], v[142:145], v[206:209], v[46:49]
	v_mfma_f32_16x16x32_bf16 v[42:45], v[156:159], v[206:209], v[42:45]
	v_mfma_f32_16x16x32_bf16 v[30:33], v[142:145], v[214:217], v[30:33]
	v_mfma_f32_16x16x32_bf16 v[26:29], v[156:159], v[214:217], v[26:29]
	v_mfma_f32_16x16x32_bf16 v[14:17], v[142:145], v[222:225], v[14:17]
	v_mfma_f32_16x16x32_bf16 v[10:13], v[156:159], v[222:225], v[10:13]
	v_mfma_f32_16x16x32_bf16 v[62:65], v[146:149], v[202:205], v[62:65]
	v_mfma_f32_16x16x32_bf16 v[58:61], v[160:163], v[202:205], v[58:61]
	v_mfma_f32_16x16x32_bf16 v[46:49], v[146:149], v[210:213], v[46:49]
	v_mfma_f32_16x16x32_bf16 v[42:45], v[160:163], v[210:213], v[42:45]
	v_mfma_f32_16x16x32_bf16 v[30:33], v[146:149], v[218:221], v[30:33]
	v_mfma_f32_16x16x32_bf16 v[26:29], v[160:163], v[218:221], v[26:29]
	v_mfma_f32_16x16x32_bf16 v[14:17], v[146:149], v[226:229], v[14:17]
	v_mfma_f32_16x16x32_bf16 v[10:13], v[160:163], v[226:229], v[10:13]
	v_mfma_f32_16x16x32_bf16 v[54:57], v[176:179], v[198:201], v[54:57]
	v_mfma_f32_16x16x32_bf16 v[50:53], v[190:193], v[198:201], v[50:53]
	v_mfma_f32_16x16x32_bf16 v[38:41], v[176:179], v[206:209], v[38:41]
	v_mfma_f32_16x16x32_bf16 v[34:37], v[190:193], v[206:209], v[34:37]
	v_mfma_f32_16x16x32_bf16 v[22:25], v[176:179], v[214:217], v[22:25]
	v_mfma_f32_16x16x32_bf16 v[18:21], v[190:193], v[214:217], v[18:21]
	v_mfma_f32_16x16x32_bf16 v[6:9], v[176:179], v[222:225], v[6:9]
	v_mfma_f32_16x16x32_bf16 v[2:5], v[190:193], v[222:225], v[2:5]
	v_mfma_f32_16x16x32_bf16 v[54:57], v[180:183], v[202:205], v[54:57]
	v_mfma_f32_16x16x32_bf16 v[50:53], v[194:197], v[202:205], v[50:53]
	v_mfma_f32_16x16x32_bf16 v[38:41], v[180:183], v[210:213], v[38:41]
	v_mfma_f32_16x16x32_bf16 v[34:37], v[194:197], v[210:213], v[34:37]
	v_mfma_f32_16x16x32_bf16 v[22:25], v[180:183], v[218:221], v[22:25]
	v_mfma_f32_16x16x32_bf16 v[18:21], v[194:197], v[218:221], v[18:21]
	v_mfma_f32_16x16x32_bf16 v[6:9], v[180:183], v[226:229], v[6:9]
	v_mfma_f32_16x16x32_bf16 v[2:5], v[194:197], v[226:229], v[2:5]
	s_setprio 0
	s_barrier
	s_add_i32 s54, 0, 0x18000
	v_add_u32_e32 v0, s54, v153
	s_add_i32 s55, 0, 0x1c000
	ds_read_b128 v[142:145], v0
	ds_read_b128 v[146:149], v0 offset:1024
	ds_read_b128 v[156:159], v0 offset:2048
	ds_read_b128 v[160:163], v0 offset:3072
	v_add_u32_e32 v0, s55, v153
	ds_read_b128 v[176:179], v0
	ds_read_b128 v[180:183], v0 offset:1024
	ds_read_b128 v[190:193], v0 offset:2048
	ds_read_b128 v[194:197], v0 offset:3072
	s_add_u32 s40, s40, 0x40000
	s_addc_u32 s41, s41, 0
	s_mov_b32 m0, s46
	ds_read_b128 v[198:201], v155 offset:32768
	ds_read_b128 v[202:205], v155 offset:33792
	ds_read_b128 v[206:209], v155 offset:34816
	ds_read_b128 v[210:213], v155 offset:35840
	ds_read_b128 v[214:217], v155 offset:36864
	ds_read_b128 v[218:221], v155 offset:37888
	ds_read_b128 v[222:225], v155 offset:38912
	ds_read_b128 v[226:229], v155 offset:39936
	global_load_lds_dwordx4 v130, s[40:41]
	v_lshl_add_u64 v[240:241], s[40:41], 0, v[134:135]
	s_mov_b32 m0, s47
	s_nop 0
	global_load_lds_dwordx4 v[240:241], off
	s_waitcnt vmcnt(8)
	s_waitcnt lgkmcnt(0)
	s_barrier
	s_setprio 1
	s_waitcnt lgkmcnt(0)
	v_mfma_f32_16x16x32_bf16 v[126:129], v[142:145], v[198:201], v[126:129]
	v_mfma_f32_16x16x32_bf16 v[122:125], v[156:159], v[198:201], v[122:125]
	v_mfma_f32_16x16x32_bf16 v[110:113], v[142:145], v[206:209], v[110:113]
	v_mfma_f32_16x16x32_bf16 v[106:109], v[156:159], v[206:209], v[106:109]
	v_mfma_f32_16x16x32_bf16 v[94:97], v[142:145], v[214:217], v[94:97]
	v_mfma_f32_16x16x32_bf16 v[90:93], v[156:159], v[214:217], v[90:93]
	v_mfma_f32_16x16x32_bf16 v[78:81], v[142:145], v[222:225], v[78:81]
	v_mfma_f32_16x16x32_bf16 v[74:77], v[156:159], v[222:225], v[74:77]
	v_mfma_f32_16x16x32_bf16 v[126:129], v[146:149], v[202:205], v[126:129]
	v_mfma_f32_16x16x32_bf16 v[122:125], v[160:163], v[202:205], v[122:125]
	v_mfma_f32_16x16x32_bf16 v[110:113], v[146:149], v[210:213], v[110:113]
	v_mfma_f32_16x16x32_bf16 v[106:109], v[160:163], v[210:213], v[106:109]
	v_mfma_f32_16x16x32_bf16 v[94:97], v[146:149], v[218:221], v[94:97]
	v_mfma_f32_16x16x32_bf16 v[90:93], v[160:163], v[218:221], v[90:93]
	v_mfma_f32_16x16x32_bf16 v[78:81], v[146:149], v[226:229], v[78:81]
	v_mfma_f32_16x16x32_bf16 v[74:77], v[160:163], v[226:229], v[74:77]
	v_mfma_f32_16x16x32_bf16 v[118:121], v[176:179], v[198:201], v[118:121]
	v_mfma_f32_16x16x32_bf16 v[114:117], v[190:193], v[198:201], v[114:117]
	v_mfma_f32_16x16x32_bf16 v[102:105], v[176:179], v[206:209], v[102:105]
	v_mfma_f32_16x16x32_bf16 v[98:101], v[190:193], v[206:209], v[98:101]
	v_mfma_f32_16x16x32_bf16 v[86:89], v[176:179], v[214:217], v[86:89]
	v_mfma_f32_16x16x32_bf16 v[82:85], v[190:193], v[214:217], v[82:85]
	v_mfma_f32_16x16x32_bf16 v[70:73], v[176:179], v[222:225], v[70:73]
	v_mfma_f32_16x16x32_bf16 v[66:69], v[190:193], v[222:225], v[66:69]
	v_mfma_f32_16x16x32_bf16 v[118:121], v[180:183], v[202:205], v[118:121]
	v_mfma_f32_16x16x32_bf16 v[114:117], v[194:197], v[202:205], v[114:117]
	v_mfma_f32_16x16x32_bf16 v[102:105], v[180:183], v[210:213], v[102:105]
	v_mfma_f32_16x16x32_bf16 v[98:101], v[194:197], v[210:213], v[98:101]
	v_mfma_f32_16x16x32_bf16 v[86:89], v[180:183], v[218:221], v[86:89]
	v_mfma_f32_16x16x32_bf16 v[82:85], v[194:197], v[218:221], v[82:85]
	v_mfma_f32_16x16x32_bf16 v[70:73], v[180:183], v[226:229], v[70:73]
	v_mfma_f32_16x16x32_bf16 v[66:69], v[194:197], v[226:229], v[66:69]
	s_setprio 0
	s_barrier
; #define PG8_STAGE(bufoff, gbase, voff) do { _Pragma("unroll") for (int _i = 0; _i < 2; ++_i) \
;         __builtin_amdgcn_global_load_lds((const unsigned*)((const char*)(gbase) + (voff)[_i]), (LAS unsigned*)(lds + (bufoff) + ldsw + _i * 8192), 16, 0, 0); } while (0)
; #define PG8_LDA(dst, b, h) do { _Pragma("unroll") for (int m = 0; m < 4; ++m) _Pragma("unroll") for (int k = 0; k < 2; ++k) dst[m][k] = *(const LAS bf16x8*)(lds + PG8_SA(b, h) + aoff + m * 2048 + k * 1024); } while (0)
; #define PG8_MMA(ai, bj, At, Bt) do { __builtin_amdgcn_s_setprio(1); _Pragma("unroll") for (int m = 0; m < 4; ++m) _Pragma("unroll") for (int n = 0; n < 2; ++n) _Pragma("unroll") for (int k = 0; k < 2; ++k) \
;         acc[ai][bj][m][n] = __builtin_amdgcn_mfma_f32_16x16x32_bf16(Bt[n][k], At[m][k], acc[ai][bj][m][n], 0, 0, 0); __builtin_amdgcn_s_setprio(0); } while (0)
; #define PG8_WAIT_V(n) asm volatile("s_waitcnt vmcnt(" #n ")" ::: "memory")
; #define PG8_WAIT_L(n) asm volatile("s_waitcnt lgkmcnt(" #n ")" ::: "memory")
; #define PG8_BAR __builtin_amdgcn_s_barrier()
; #define PG8_SCHED __builtin_amdgcn_sched_barrier(0)
; template <class Epi>
; DI void gemm_phase(int wid0, LAS unsigned char* lds, const Gemm g, const StaticOrder& S, const Epi& E) {
;     ...
;             PG8_LDA(At, 1, 1); PG8_STAGE(PG8_SB(1, 0), b3, voffB); PG8_STAGE(PG8_SB(1, 1), b3 + hstep, voffB); PG8_STAGE(PG8_SA(1, 0), a3, voffA);
;             PG8_WAIT_V(8); PG8_WAIT_L(0); PG8_BAR; PG8_MMA(1, 0, At, B0); PG8_MMA(1, 1, At, B1); PG8_BAR; PG8_SCHED;
;         }
	s_add_i32 s40, s54, s2
	v_lshl_add_u64 v[150:151], v[150:151], 0, s[30:31]
	s_mov_b32 m0, s40
	ds_read_b128 v[198:201], v155 offset:49152
	ds_read_b128 v[202:205], v155 offset:50176
	ds_read_b128 v[206:209], v155 offset:51200
	ds_read_b128 v[210:213], v155 offset:52224
	ds_read_b128 v[214:217], v155 offset:53248
	ds_read_b128 v[218:221], v155 offset:54272
	ds_read_b128 v[222:225], v155 offset:55296
	ds_read_b128 v[226:229], v155 offset:56320
	global_load_lds_dwordx4 v[150:151], off
	s_add_i32 m0, s40, 0x2000
	s_add_u32 s38, s38, 0x40080
	v_lshl_add_u64 v[150:151], v[230:231], 0, s[30:31]
	s_addc_u32 s39, s39, 0
	s_add_i32 s40, s55, s2
	global_load_lds_dwordx4 v[150:151], off
	s_mov_b32 m0, s40
	s_nop 0
	global_load_lds_dwordx4 v132, s[38:39]
	s_add_i32 m0, s40, 0x2000
	s_nop 0
	global_load_lds_dwordx4 v136, s[38:39]
	v_lshl_add_u64 v[150:151], v[236:237], 0, s[30:31]
	s_mov_b32 m0, s48
	s_nop 0
	global_load_lds_dwordx4 v[150:151], off
	v_lshl_add_u64 v[150:151], v[238:239], 0, s[30:31]
	s_mov_b32 m0, s49
	s_nop 0
	global_load_lds_dwordx4 v[150:151], off
	s_waitcnt vmcnt(8)
	s_waitcnt lgkmcnt(0)
	s_barrier
	s_setprio 1
	s_waitcnt lgkmcnt(0)
	v_mfma_f32_16x16x32_bf16 v[62:65], v[142:145], v[198:201], v[62:65]
	v_mfma_f32_16x16x32_bf16 v[58:61], v[156:159], v[198:201], v[58:61]
	v_mfma_f32_16x16x32_bf16 v[46:49], v[142:145], v[206:209], v[46:49]
	v_mfma_f32_16x16x32_bf16 v[42:45], v[156:159], v[206:209], v[42:45]
	v_mfma_f32_16x16x32_bf16 v[30:33], v[142:145], v[214:217], v[30:33]
	v_mfma_f32_16x16x32_bf16 v[26:29], v[156:159], v[214:217], v[26:29]
	v_mfma_f32_16x16x32_bf16 v[14:17], v[142:145], v[222:225], v[14:17]
	v_mfma_f32_16x16x32_bf16 v[10:13], v[156:159], v[222:225], v[10:13]
	v_mfma_f32_16x16x32_bf16 v[62:65], v[146:149], v[202:205], v[62:65]
	v_mfma_f32_16x16x32_bf16 v[58:61], v[160:163], v[202:205], v[58:61]
	v_mfma_f32_16x16x32_bf16 v[46:49], v[146:149], v[210:213], v[46:49]
	v_mfma_f32_16x16x32_bf16 v[42:45], v[160:163], v[210:213], v[42:45]
	v_mfma_f32_16x16x32_bf16 v[30:33], v[146:149], v[218:221], v[30:33]
	v_mfma_f32_16x16x32_bf16 v[26:29], v[160:163], v[218:221], v[26:29]
	v_mfma_f32_16x16x32_bf16 v[14:17], v[146:149], v[226:229], v[14:17]
	v_mfma_f32_16x16x32_bf16 v[10:13], v[160:163], v[226:229], v[10:13]
	v_mfma_f32_16x16x32_bf16 v[54:57], v[176:179], v[198:201], v[54:57]
	v_mfma_f32_16x16x32_bf16 v[50:53], v[190:193], v[198:201], v[50:53]
	v_mfma_f32_16x16x32_bf16 v[38:41], v[176:179], v[206:209], v[38:41]
	v_mfma_f32_16x16x32_bf16 v[34:37], v[190:193], v[206:209], v[34:37]
	v_mfma_f32_16x16x32_bf16 v[22:25], v[176:179], v[214:217], v[22:25]
	v_mfma_f32_16x16x32_bf16 v[18:21], v[190:193], v[214:217], v[18:21]
	v_mfma_f32_16x16x32_bf16 v[6:9], v[176:179], v[222:225], v[6:9]
	v_mfma_f32_16x16x32_bf16 v[2:5], v[190:193], v[222:225], v[2:5]
	v_mfma_f32_16x16x32_bf16 v[54:57], v[180:183], v[202:205], v[54:57]
	v_mfma_f32_16x16x32_bf16 v[50:53], v[194:197], v[202:205], v[50:53]
	v_mfma_f32_16x16x32_bf16 v[38:41], v[180:183], v[210:213], v[38:41]
	v_mfma_f32_16x16x32_bf16 v[34:37], v[194:197], v[210:213], v[34:37]
	v_mfma_f32_16x16x32_bf16 v[22:25], v[180:183], v[218:221], v[22:25]
	v_mfma_f32_16x16x32_bf16 v[18:21], v[194:197], v[218:221], v[18:21]
	v_mfma_f32_16x16x32_bf16 v[6:9], v[180:183], v[226:229], v[6:9]
	v_mfma_f32_16x16x32_bf16 v[2:5], v[194:197], v[226:229], v[2:5]
	s_setprio 0
	s_barrier
	s_add_i32 s51, s51, 2
	s_add_u32 s28, s28, 0x100
	s_addc_u32 s29, s29, 0
	s_add_u32 s17, s17, 0x100
	s_addc_u32 s19, s19, 0
	s_cmp_gt_u32 s51, 13
	s_cbranch_scc0 .LBB0_277
	s_and_b64 vcc, exec, s[14:15]
	s_cbranch_vccz .LBB0_280
	s_barrier
